# speedup vs baseline: 1.0062x; 1.0058x over previous
; DI float frcp(float x) { return __builtin_amdgcn_rcpf(x); }
; DI u32x2 pack4(const f32x4 a) { u32x2 w; w.x = cvt_pk_bf16(a[0], a[1]); w.y = cvt_pk_bf16(a[2], a[3]); return w; }
; template <int N> DI float row_shift(float cur, float prev) {
;     const int t = __builtin_amdgcn_update_dpp(0, __float_as_int(prev), 0x120 + N, 0xf, 0xf, false);
;     return __int_as_float(__builtin_amdgcn_update_dpp(t, __float_as_int(cur), 0x110 + N, 0xf, 0xf, false));
; }
;     DI void operator()(const pg8::f32x4 (&acc)[2][2][4][2], const pg8::Unit& u, int wr, int wc, int fr, int fq) const {
;     ...
;                     const f32x4 cg = acc[ai][0][m][q], cv = acc[ai][1][m][q];
;                     const f32x4 pg = m > 0 ? acc[ai][0][m > 0 ? m - 1 : 0][q] : (f32x4){0.f, 0.f, 0.f, 0.f}, pv = m > 0 ? acc[ai][1][m > 0 ? m - 1 : 0][q] : (f32x4){0.f, 0.f, 0.f, 0.f};
;                     f32x4 o;
; #pragma unroll
;                     for (int e = 0; e < 4; ++e) {
;                         const float g1 = row_shift<1>(cg[e], pg[e]), g2 = row_shift<2>(cg[e], pg[e]), v1 = row_shift<1>(cv[e], pv[e]), v2 = row_shift<2>(cv[e], pv[e]);
;                         const float a = bg[e] + kg0[e] * g2 + kg1[e] * g1 + kg2[e] * cg[e], b = bv[e] + kv0[e] * v2 + kv1[e] * v1 + kv2[e] * cv[e];
;                         o[e] = a * frcp(1.f + __expf(-a)) * b;
;                     }
;                     const int r = u.pm * 256 + ai * 128 + wr * 64 + m * 16 + fr;
;                     if (m > 0 || fr >= 2) *(u32x2*)(ACT + (size_t)r * DFF + j0 + 4 * q) = pack4(o);
.LBB0_832:
	s_or_b64 exec, exec, s[40:41]
	v_mov_b32_dpp v143, v127 row_ror:2 row_mask:0xf bank_mask:0xf
	v_mov_b32_dpp v142, v119 row_ror:2 row_mask:0xf bank_mask:0xf
	v_mov_b32_dpp v141, v127 row_ror:1 row_mask:0xf bank_mask:0xf
	v_mov_b32_dpp v143, v111 row_shr:2 row_mask:0xf bank_mask:0xf
	v_mov_b32_dpp v140, v119 row_ror:1 row_mask:0xf bank_mask:0xf
	v_mov_b32_dpp v142, v103 row_shr:2 row_mask:0xf bank_mask:0xf
	v_mov_b32_dpp v141, v111 row_shr:1 row_mask:0xf bank_mask:0xf
	v_mov_b32_dpp v140, v103 row_shr:1 row_mask:0xf bank_mask:0xf
	v_pk_fma_f32 v[142:143], v[212:213], v[142:143], v[214:215]
	v_mov_b32_e32 v144, v103
	v_mov_b32_e32 v145, v111
	v_pk_fma_f32 v[140:141], v[210:211], v[140:141], v[142:143]
	v_pk_fma_f32 v[140:141], v[144:145], v[208:209], v[140:141]
	v_mul_f32_e32 v138, 0xbfb8aa3b, v141
	v_exp_f32_e32 v142, v138
	v_mov_b32_dpp v139, v126 row_ror:2 row_mask:0xf bank_mask:0xf
	v_mov_b32_dpp v138, v118 row_ror:2 row_mask:0xf bank_mask:0xf
	v_mov_b32_dpp v137, v126 row_ror:1 row_mask:0xf bank_mask:0xf
	v_mov_b32_dpp v139, v110 row_shr:2 row_mask:0xf bank_mask:0xf
	v_mov_b32_dpp v136, v118 row_ror:1 row_mask:0xf bank_mask:0xf
	v_mov_b32_dpp v138, v102 row_shr:2 row_mask:0xf bank_mask:0xf
	v_mov_b32_dpp v137, v110 row_shr:1 row_mask:0xf bank_mask:0xf
	v_mov_b32_dpp v136, v102 row_shr:1 row_mask:0xf bank_mask:0xf
	v_add_f32_e32 v142, 1.0, v142
	v_pk_fma_f32 v[138:139], v[218:219], v[138:139], v[216:217]
	v_rcp_f32_e32 v144, v142
	v_mov_b32_e32 v142, v102
	v_mov_b32_e32 v143, v110
	v_pk_fma_f32 v[136:137], v[220:221], v[136:137], v[138:139]
	v_pk_fma_f32 v[136:137], v[142:143], v[222:223], v[136:137]
	v_mul_f32_e32 v138, 0xbfb8aa3b, v137
	v_exp_f32_e32 v138, v138
	v_mov_b32_dpp v135, v125 row_ror:2 row_mask:0xf bank_mask:0xf
	v_mov_b32_dpp v134, v117 row_ror:2 row_mask:0xf bank_mask:0xf
	v_mov_b32_dpp v133, v125 row_ror:1 row_mask:0xf bank_mask:0xf
	v_mov_b32_dpp v135, v109 row_shr:2 row_mask:0xf bank_mask:0xf
	v_mov_b32_dpp v132, v117 row_ror:1 row_mask:0xf bank_mask:0xf
	v_mov_b32_dpp v134, v101 row_shr:2 row_mask:0xf bank_mask:0xf
	v_mov_b32_dpp v133, v109 row_shr:1 row_mask:0xf bank_mask:0xf
	v_mov_b32_dpp v132, v101 row_shr:1 row_mask:0xf bank_mask:0xf
	v_mul_f32_e32 v139, v141, v144
	v_add_f32_e32 v138, 1.0, v138
	v_pk_fma_f32 v[134:135], v[196:197], v[134:135], v[198:199]
	v_mov_b32_dpp v131, v124 row_ror:2 row_mask:0xf bank_mask:0xf
	v_mov_b32_dpp v130, v116 row_ror:2 row_mask:0xf bank_mask:0xf
	v_mul_f32_e32 v140, v140, v139
	v_rcp_f32_e32 v141, v138
	v_mov_b32_e32 v138, v101
	v_mov_b32_e32 v139, v109
	v_pk_fma_f32 v[132:133], v[194:195], v[132:133], v[134:135]
	v_mov_b32_dpp v129, v124 row_ror:1 row_mask:0xf bank_mask:0xf
	v_mov_b32_dpp v131, v108 row_shr:2 row_mask:0xf bank_mask:0xf
	v_mov_b32_dpp v128, v116 row_ror:1 row_mask:0xf bank_mask:0xf
	v_mov_b32_dpp v130, v100 row_shr:2 row_mask:0xf bank_mask:0xf
	v_pk_fma_f32 v[132:133], v[138:139], v[192:193], v[132:133]
	v_mov_b32_dpp v129, v108 row_shr:1 row_mask:0xf bank_mask:0xf
	v_mov_b32_dpp v128, v100 row_shr:1 row_mask:0xf bank_mask:0xf
	v_mul_f32_e32 v134, 0xbfb8aa3b, v133
	v_pk_fma_f32 v[130:131], v[202:203], v[130:131], v[200:201]
	v_exp_f32_e32 v138, v134
	v_mov_b32_e32 v134, v100
	v_mov_b32_e32 v135, v108
	v_pk_fma_f32 v[128:129], v[204:205], v[128:129], v[130:131]
	v_mul_f32_e32 v131, v137, v141
	v_pk_fma_f32 v[128:129], v[134:135], v[206:207], v[128:129]
	v_add_f32_e32 v134, 1.0, v138
	v_mul_f32_e32 v130, 0xbfb8aa3b, v129
	v_exp_f32_e32 v130, v130
	v_rcp_f32_e32 v134, v134
	v_mul_f32_e32 v131, v136, v131
	v_add_f32_e32 v130, 1.0, v130
	v_rcp_f32_e32 v130, v130
	v_mul_f32_e32 v133, v133, v134
	v_mul_f32_e32 v132, v132, v133
	v_mul_f32_e32 v129, v129, v130
	v_mul_f32_e32 v128, v128, v129
	v_add_u32_e32 v129, 16, v164
	v_cvt_pk_bf16_f32 v132, v128, v132
	v_cvt_pk_bf16_f32 v133, v131, v140
	v_mov_b64_e32 v[130:131], s[66:67]
	v_mad_i64_i32 v[134:135], s[14:15], v129, s97, v[130:131]
	v_lshlrev_b64 v[128:129], 1, v[178:179]
	v_lshl_add_u64 v[182:183], v[134:135], 0, v[128:129]
	global_store_dwordx2 v[182:183], v[132:133], off
	v_mov_b32_dpp v147, v111 row_ror:2 row_mask:0xf bank_mask:0xf
	v_mov_b32_dpp v146, v103 row_ror:2 row_mask:0xf bank_mask:0xf
	v_mov_b32_dpp v145, v111 row_ror:1 row_mask:0xf bank_mask:0xf
	v_mov_b32_dpp v147, v95 row_shr:2 row_mask:0xf bank_mask:0xf
	v_mov_b32_dpp v144, v103 row_ror:1 row_mask:0xf bank_mask:0xf
	v_mov_b32_dpp v146, v87 row_shr:2 row_mask:0xf bank_mask:0xf
	v_mov_b32_dpp v145, v95 row_shr:1 row_mask:0xf bank_mask:0xf
	v_mov_b32_dpp v144, v87 row_shr:1 row_mask:0xf bank_mask:0xf
	v_pk_fma_f32 v[146:147], v[212:213], v[146:147], v[214:215]
	v_mov_b32_e32 v148, v87
	v_mov_b32_e32 v149, v95
	v_pk_fma_f32 v[144:145], v[210:211], v[144:145], v[146:147]
	v_pk_fma_f32 v[144:145], v[148:149], v[208:209], v[144:145]
	v_mul_f32_e32 v142, 0xbfb8aa3b, v145
	v_exp_f32_e32 v146, v142
	v_mov_b32_dpp v143, v110 row_ror:2 row_mask:0xf bank_mask:0xf
	v_mov_b32_dpp v142, v102 row_ror:2 row_mask:0xf bank_mask:0xf
	v_mov_b32_dpp v141, v110 row_ror:1 row_mask:0xf bank_mask:0xf
	v_mov_b32_dpp v143, v94 row_shr:2 row_mask:0xf bank_mask:0xf
	v_mov_b32_dpp v140, v102 row_ror:1 row_mask:0xf bank_mask:0xf
	v_mov_b32_dpp v142, v86 row_shr:2 row_mask:0xf bank_mask:0xf
	v_mov_b32_dpp v141, v94 row_shr:1 row_mask:0xf bank_mask:0xf
	v_mov_b32_dpp v140, v86 row_shr:1 row_mask:0xf bank_mask:0xf
	v_add_f32_e32 v146, 1.0, v146
	v_pk_fma_f32 v[142:143], v[218:219], v[142:143], v[216:217]
	v_rcp_f32_e32 v148, v146
	v_mov_b32_e32 v146, v86
	v_mov_b32_e32 v147, v94
	v_pk_fma_f32 v[140:141], v[220:221], v[140:141], v[142:143]
	v_pk_fma_f32 v[140:141], v[146:147], v[222:223], v[140:141]
; DI float frcp(float x) { return __builtin_amdgcn_rcpf(x); }
; DI u32x2 pack4(const f32x4 a) { u32x2 w; w.x = cvt_pk_bf16(a[0], a[1]); w.y = cvt_pk_bf16(a[2], a[3]); return w; }
; template <int N> DI float row_shift(float cur, float prev) {
;     const int t = __builtin_amdgcn_update_dpp(0, __float_as_int(prev), 0x120 + N, 0xf, 0xf, false);
;     return __int_as_float(__builtin_amdgcn_update_dpp(t, __float_as_int(cur), 0x110 + N, 0xf, 0xf, false));
; }
;     DI void operator()(const pg8::f32x4 (&acc)[2][2][4][2], const pg8::Unit& u, int wr, int wc, int fr, int fq) const {
;     ...
;                     const f32x4 cg = acc[ai][0][m][q], cv = acc[ai][1][m][q];
;                     const f32x4 pg = m > 0 ? acc[ai][0][m > 0 ? m - 1 : 0][q] : (f32x4){0.f, 0.f, 0.f, 0.f}, pv = m > 0 ? acc[ai][1][m > 0 ? m - 1 : 0][q] : (f32x4){0.f, 0.f, 0.f, 0.f};
;                     f32x4 o;
; #pragma unroll
;                     for (int e = 0; e < 4; ++e) {
;                         const float g1 = row_shift<1>(cg[e], pg[e]), g2 = row_shift<2>(cg[e], pg[e]), v1 = row_shift<1>(cv[e], pv[e]), v2 = row_shift<2>(cv[e], pv[e]);
;                         const float a = bg[e] + kg0[e] * g2 + kg1[e] * g1 + kg2[e] * cg[e], b = bv[e] + kv0[e] * v2 + kv1[e] * v1 + kv2[e] * cv[e];
;                         o[e] = a * frcp(1.f + __expf(-a)) * b;
;                     }
;                     const int r = u.pm * 256 + ai * 128 + wr * 64 + m * 16 + fr;
;                     if (m > 0 || fr >= 2) *(u32x2*)(ACT + (size_t)r * DFF + j0 + 4 * q) = pack4(o);
	v_mul_f32_e32 v142, 0xbfb8aa3b, v141
	v_exp_f32_e32 v142, v142
	v_mov_b32_dpp v139, v109 row_ror:2 row_mask:0xf bank_mask:0xf
	v_mov_b32_dpp v138, v101 row_ror:2 row_mask:0xf bank_mask:0xf
	v_mov_b32_dpp v137, v109 row_ror:1 row_mask:0xf bank_mask:0xf
	v_mov_b32_dpp v139, v93 row_shr:2 row_mask:0xf bank_mask:0xf
	v_mov_b32_dpp v136, v101 row_ror:1 row_mask:0xf bank_mask:0xf
	v_mov_b32_dpp v138, v85 row_shr:2 row_mask:0xf bank_mask:0xf
	v_mov_b32_dpp v137, v93 row_shr:1 row_mask:0xf bank_mask:0xf
	v_mov_b32_dpp v136, v85 row_shr:1 row_mask:0xf bank_mask:0xf
	v_mul_f32_e32 v143, v145, v148
	v_add_f32_e32 v142, 1.0, v142
	v_pk_fma_f32 v[138:139], v[196:197], v[138:139], v[198:199]
	v_mov_b32_dpp v135, v108 row_ror:2 row_mask:0xf bank_mask:0xf
	v_mov_b32_dpp v134, v100 row_ror:2 row_mask:0xf bank_mask:0xf
	v_mul_f32_e32 v144, v144, v143
	v_rcp_f32_e32 v145, v142
	v_mov_b32_e32 v142, v85
	v_mov_b32_e32 v143, v93
	v_pk_fma_f32 v[136:137], v[194:195], v[136:137], v[138:139]
	v_mov_b32_dpp v133, v108 row_ror:1 row_mask:0xf bank_mask:0xf
	v_mov_b32_dpp v135, v92 row_shr:2 row_mask:0xf bank_mask:0xf
	v_mov_b32_dpp v132, v100 row_ror:1 row_mask:0xf bank_mask:0xf
	v_mov_b32_dpp v134, v84 row_shr:2 row_mask:0xf bank_mask:0xf
	v_pk_fma_f32 v[136:137], v[142:143], v[192:193], v[136:137]
	v_mov_b32_dpp v133, v92 row_shr:1 row_mask:0xf bank_mask:0xf
	v_mov_b32_dpp v132, v84 row_shr:1 row_mask:0xf bank_mask:0xf
	v_mul_f32_e32 v138, 0xbfb8aa3b, v137
	v_pk_fma_f32 v[134:135], v[202:203], v[134:135], v[200:201]
	v_exp_f32_e32 v142, v138
	v_mov_b32_e32 v138, v84
	v_mov_b32_e32 v139, v92
	v_pk_fma_f32 v[132:133], v[204:205], v[132:133], v[134:135]
	v_mul_f32_e32 v135, v141, v145
	v_pk_fma_f32 v[132:133], v[138:139], v[206:207], v[132:133]
	v_add_f32_e32 v138, 1.0, v142
	v_mul_f32_e32 v134, 0xbfb8aa3b, v133
	v_exp_f32_e32 v134, v134
	v_rcp_f32_e32 v138, v138
	v_mul_f32_e32 v135, v140, v135
	v_add_f32_e32 v134, 1.0, v134
	v_rcp_f32_e32 v134, v134
	v_mul_f32_e32 v137, v137, v138
	v_mul_f32_e32 v136, v136, v137
	v_mul_f32_e32 v133, v133, v134
	v_mul_f32_e32 v132, v132, v133
	v_add_u32_e32 v134, 32, v164
	v_cvt_pk_bf16_f32 v132, v132, v136
	v_cvt_pk_bf16_f32 v133, v135, v144
	v_mad_i64_i32 v[134:135], s[14:15], v134, s97, v[130:131]
	v_lshl_add_u64 v[184:185], v[134:135], 0, v[128:129]
	global_store_dwordx2 v[184:185], v[132:133], off
	v_mov_b32_dpp v147, v95 row_ror:2 row_mask:0xf bank_mask:0xf
	v_mov_b32_dpp v146, v87 row_ror:2 row_mask:0xf bank_mask:0xf
	v_mov_b32_dpp v145, v95 row_ror:1 row_mask:0xf bank_mask:0xf
	v_mov_b32_dpp v147, v79 row_shr:2 row_mask:0xf bank_mask:0xf
	v_mov_b32_dpp v144, v87 row_ror:1 row_mask:0xf bank_mask:0xf
	v_mov_b32_dpp v146, v71 row_shr:2 row_mask:0xf bank_mask:0xf
	v_mov_b32_dpp v145, v79 row_shr:1 row_mask:0xf bank_mask:0xf
	v_mov_b32_dpp v144, v71 row_shr:1 row_mask:0xf bank_mask:0xf
	v_pk_fma_f32 v[146:147], v[212:213], v[146:147], v[214:215]
	v_mov_b32_e32 v148, v71
	v_mov_b32_e32 v149, v79
	v_pk_fma_f32 v[144:145], v[210:211], v[144:145], v[146:147]
	v_pk_fma_f32 v[144:145], v[148:149], v[208:209], v[144:145]
	v_mul_f32_e32 v142, 0xbfb8aa3b, v145
	v_exp_f32_e32 v146, v142
	v_mov_b32_dpp v143, v94 row_ror:2 row_mask:0xf bank_mask:0xf
	v_mov_b32_dpp v142, v86 row_ror:2 row_mask:0xf bank_mask:0xf
	v_mov_b32_dpp v141, v94 row_ror:1 row_mask:0xf bank_mask:0xf
	v_mov_b32_dpp v143, v78 row_shr:2 row_mask:0xf bank_mask:0xf
	v_mov_b32_dpp v140, v86 row_ror:1 row_mask:0xf bank_mask:0xf
	v_mov_b32_dpp v142, v70 row_shr:2 row_mask:0xf bank_mask:0xf
	v_mov_b32_dpp v141, v78 row_shr:1 row_mask:0xf bank_mask:0xf
	v_mov_b32_dpp v140, v70 row_shr:1 row_mask:0xf bank_mask:0xf
	v_add_f32_e32 v146, 1.0, v146
	v_pk_fma_f32 v[142:143], v[218:219], v[142:143], v[216:217]
	v_rcp_f32_e32 v148, v146
	v_mov_b32_e32 v146, v70
	v_mov_b32_e32 v147, v78
	v_pk_fma_f32 v[140:141], v[220:221], v[140:141], v[142:143]
	v_pk_fma_f32 v[140:141], v[146:147], v[222:223], v[140:141]
	v_mul_f32_e32 v142, 0xbfb8aa3b, v141
	v_exp_f32_e32 v142, v142
	v_mov_b32_dpp v139, v93 row_ror:2 row_mask:0xf bank_mask:0xf
	v_mov_b32_dpp v138, v85 row_ror:2 row_mask:0xf bank_mask:0xf
	v_mov_b32_dpp v137, v93 row_ror:1 row_mask:0xf bank_mask:0xf
	v_mov_b32_dpp v139, v77 row_shr:2 row_mask:0xf bank_mask:0xf
	v_mov_b32_dpp v136, v85 row_ror:1 row_mask:0xf bank_mask:0xf
	v_mov_b32_dpp v138, v69 row_shr:2 row_mask:0xf bank_mask:0xf
	v_mov_b32_dpp v137, v77 row_shr:1 row_mask:0xf bank_mask:0xf
	v_mov_b32_dpp v136, v69 row_shr:1 row_mask:0xf bank_mask:0xf
	v_mul_f32_e32 v143, v145, v148
	v_add_f32_e32 v142, 1.0, v142
	v_pk_fma_f32 v[138:139], v[196:197], v[138:139], v[198:199]
	v_mov_b32_dpp v135, v92 row_ror:2 row_mask:0xf bank_mask:0xf
	v_mov_b32_dpp v134, v84 row_ror:2 row_mask:0xf bank_mask:0xf
	v_mul_f32_e32 v144, v144, v143
	v_rcp_f32_e32 v145, v142
	v_mov_b32_e32 v142, v69
	v_mov_b32_e32 v143, v77
	v_pk_fma_f32 v[136:137], v[194:195], v[136:137], v[138:139]
	v_mov_b32_dpp v133, v92 row_ror:1 row_mask:0xf bank_mask:0xf
	v_mov_b32_dpp v135, v76 row_shr:2 row_mask:0xf bank_mask:0xf
	v_mov_b32_dpp v132, v84 row_ror:1 row_mask:0xf bank_mask:0xf
	v_mov_b32_dpp v134, v68 row_shr:2 row_mask:0xf bank_mask:0xf
	v_pk_fma_f32 v[136:137], v[142:143], v[192:193], v[136:137]
	v_mov_b32_dpp v133, v76 row_shr:1 row_mask:0xf bank_mask:0xf
	v_mov_b32_dpp v132, v68 row_shr:1 row_mask:0xf bank_mask:0xf
	v_mul_f32_e32 v138, 0xbfb8aa3b, v137
	v_pk_fma_f32 v[134:135], v[202:203], v[134:135], v[200:201]
	v_exp_f32_e32 v142, v138
	v_mov_b32_e32 v138, v68
	v_mov_b32_e32 v139, v76
	v_pk_fma_f32 v[132:133], v[204:205], v[132:133], v[134:135]
	v_mul_f32_e32 v135, v141, v145
	v_pk_fma_f32 v[132:133], v[138:139], v[206:207], v[132:133]
; DI float frcp(float x) { return __builtin_amdgcn_rcpf(x); }
; DI u32x2 pack4(const f32x4 a) { u32x2 w; w.x = cvt_pk_bf16(a[0], a[1]); w.y = cvt_pk_bf16(a[2], a[3]); return w; }
; template <int N> DI float row_shift(float cur, float prev) {
;     const int t = __builtin_amdgcn_update_dpp(0, __float_as_int(prev), 0x120 + N, 0xf, 0xf, false);
;     return __int_as_float(__builtin_amdgcn_update_dpp(t, __float_as_int(cur), 0x110 + N, 0xf, 0xf, false));
; }
;     DI void operator()(const pg8::f32x4 (&acc)[2][2][4][2], const pg8::Unit& u, int wr, int wc, int fr, int fq) const {
;     ...
;                     const f32x4 cg = acc[ai][0][m][q], cv = acc[ai][1][m][q];
;                     const f32x4 pg = m > 0 ? acc[ai][0][m > 0 ? m - 1 : 0][q] : (f32x4){0.f, 0.f, 0.f, 0.f}, pv = m > 0 ? acc[ai][1][m > 0 ? m - 1 : 0][q] : (f32x4){0.f, 0.f, 0.f, 0.f};
;                     f32x4 o;
; #pragma unroll
;                     for (int e = 0; e < 4; ++e) {
;                         const float g1 = row_shift<1>(cg[e], pg[e]), g2 = row_shift<2>(cg[e], pg[e]), v1 = row_shift<1>(cv[e], pv[e]), v2 = row_shift<2>(cv[e], pv[e]);
;                         const float a = bg[e] + kg0[e] * g2 + kg1[e] * g1 + kg2[e] * cg[e], b = bv[e] + kv0[e] * v2 + kv1[e] * v1 + kv2[e] * cv[e];
;                         o[e] = a * frcp(1.f + __expf(-a)) * b;
;                     }
;                     const int r = u.pm * 256 + ai * 128 + wr * 64 + m * 16 + fr;
;                     if (m > 0 || fr >= 2) *(u32x2*)(ACT + (size_t)r * DFF + j0 + 4 * q) = pack4(o);
;                     __builtin_amdgcn_sched_barrier(0);
;                 }
	v_add_f32_e32 v138, 1.0, v142
	v_mul_f32_e32 v134, 0xbfb8aa3b, v133
	v_exp_f32_e32 v134, v134
	v_rcp_f32_e32 v138, v138
	v_mad_i64_i32 v[130:131], s[14:15], v230, s97, v[130:131]
	v_add_f32_e32 v134, 1.0, v134
	v_rcp_f32_e32 v134, v134
	v_mul_f32_e32 v137, v137, v138
	v_mul_f32_e32 v135, v140, v135
	v_mul_f32_e32 v136, v136, v137
	v_mul_f32_e32 v133, v133, v134
	v_mul_f32_e32 v132, v132, v133
	v_lshl_add_u64 v[186:187], v[130:131], 0, v[128:129]
	v_cvt_pk_bf16_f32 v132, v132, v136
	v_cvt_pk_bf16_f32 v133, v135, v144
	global_store_dwordx2 v[186:187], v[132:133], off
	v_mov_b32_e32 v138, v161
	v_mov_b32_e32 v144, v161
	s_nop 0
	v_mov_b32_dpp v138, v138 row_ror:1 row_mask:0xf bank_mask:0xf
	v_mov_b32_dpp v144, v144 row_ror:2 row_mask:0xf bank_mask:0xf
	v_mov_b32_e32 v131, v138
	v_mov_b32_e32 v133, v144
	v_mov_b32_e32 v130, v138
	v_mov_b32_e32 v132, v144
	v_mov_b32_e32 v135, v138
	v_mov_b32_e32 v137, v144
	v_mov_b32_e32 v134, v138
	v_mov_b32_e32 v136, v144
	v_mov_b32_e32 v141, v138
	v_mov_b32_e32 v143, v144
	v_mov_b32_e32 v140, v138
	v_mov_b32_e32 v142, v144
	v_mov_b32_e32 v139, v138
	v_mov_b32_e32 v145, v144
	v_mov_b32_dpp v131, v60 row_shr:1 row_mask:0xf bank_mask:0xf
	v_mov_b32_dpp v133, v60 row_shr:2 row_mask:0xf bank_mask:0xf
	v_mov_b32_dpp v130, v52 row_shr:1 row_mask:0xf bank_mask:0xf
	v_mov_b32_dpp v132, v52 row_shr:2 row_mask:0xf bank_mask:0xf
	v_mov_b32_dpp v135, v61 row_shr:1 row_mask:0xf bank_mask:0xf
	v_mov_b32_dpp v137, v61 row_shr:2 row_mask:0xf bank_mask:0xf
	v_mov_b32_dpp v134, v53 row_shr:1 row_mask:0xf bank_mask:0xf
	v_mov_b32_dpp v136, v53 row_shr:2 row_mask:0xf bank_mask:0xf
	v_mov_b32_dpp v141, v62 row_shr:1 row_mask:0xf bank_mask:0xf
	v_mov_b32_dpp v143, v62 row_shr:2 row_mask:0xf bank_mask:0xf
	v_mov_b32_dpp v140, v54 row_shr:1 row_mask:0xf bank_mask:0xf
	v_mov_b32_dpp v142, v54 row_shr:2 row_mask:0xf bank_mask:0xf
	v_mov_b32_dpp v139, v63 row_shr:1 row_mask:0xf bank_mask:0xf
	v_mov_b32_dpp v145, v63 row_shr:2 row_mask:0xf bank_mask:0xf
	v_mov_b32_dpp v138, v55 row_shr:1 row_mask:0xf bank_mask:0xf
	v_mov_b32_dpp v144, v55 row_shr:2 row_mask:0xf bank_mask:0xf
	s_and_saveexec_b64 s[40:41], vcc
	s_cbranch_execz .LBB0_834
	v_pk_fma_f32 v[144:145], v[212:213], v[144:145], v[214:215]
	v_mov_b32_e32 v146, v55
	v_mov_b32_e32 v147, v63
	v_pk_fma_f32 v[138:139], v[210:211], v[138:139], v[144:145]
	v_pk_fma_f32 v[142:143], v[218:219], v[142:143], v[216:217]
	v_pk_fma_f32 v[138:139], v[146:147], v[208:209], v[138:139]
	v_pk_fma_f32 v[140:141], v[220:221], v[140:141], v[142:143]
	v_mul_f32_e32 v144, 0xbfb8aa3b, v139
	v_exp_f32_e32 v145, v144
	v_mov_b32_e32 v144, v54
	v_pk_fma_f32 v[136:137], v[196:197], v[136:137], v[198:199]
	v_pk_fma_f32 v[132:133], v[202:203], v[132:133], v[200:201]
	v_add_f32_e32 v145, 1.0, v145
	v_rcp_f32_e32 v146, v145
	v_mov_b32_e32 v145, v62
	v_pk_fma_f32 v[140:141], v[144:145], v[222:223], v[140:141]
	v_pk_fma_f32 v[134:135], v[194:195], v[134:135], v[136:137]
	v_mul_f32_e32 v142, 0xbfb8aa3b, v141
	v_exp_f32_e32 v142, v142
	v_mul_f32_e32 v139, v139, v146
	v_mul_f32_e32 v143, v138, v139
	v_mov_b32_e32 v139, v61
	v_add_f32_e32 v138, 1.0, v142
	v_rcp_f32_e32 v142, v138
	v_mov_b32_e32 v138, v53
	v_pk_fma_f32 v[134:135], v[138:139], v[192:193], v[134:135]
	v_mov_b32_e32 v137, v60
	v_mul_f32_e32 v136, 0xbfb8aa3b, v135
	v_exp_f32_e32 v138, v136
	v_mov_b32_e32 v136, v52
	v_pk_fma_f32 v[130:131], v[204:205], v[130:131], v[132:133]
	v_mul_f32_e32 v133, v141, v142
	v_pk_fma_f32 v[130:131], v[136:137], v[206:207], v[130:131]
	v_add_f32_e32 v136, 1.0, v138
	v_mul_f32_e32 v132, 0xbfb8aa3b, v131
	v_exp_f32_e32 v132, v132
	v_rcp_f32_e32 v136, v136
	v_mul_f32_e32 v133, v140, v133
	v_add_f32_e32 v132, 1.0, v132
	v_rcp_f32_e32 v132, v132
	v_mul_f32_e32 v135, v135, v136
	v_mul_f32_e32 v134, v134, v135
	v_mul_f32_e32 v131, v131, v132
	v_mul_f32_e32 v130, v130, v131
	v_cvt_pk_bf16_f32 v130, v130, v134
	v_cvt_pk_bf16_f32 v131, v133, v143
	v_mov_b64_e32 v[132:133], s[66:67]
	v_mad_i64_i32 v[132:133], s[14:15], v163, s97, v[132:133]
	v_lshl_add_u64 v[132:133], v[178:179], 1, v[132:133]
	global_store_dwordx2 v[132:133], v[130:131], off
.LBB0_834:
	s_or_b64 exec, exec, s[40:41]
	v_mov_b32_dpp v145, v63 row_ror:2 row_mask:0xf bank_mask:0xf
	v_mov_b32_dpp v144, v55 row_ror:2 row_mask:0xf bank_mask:0xf
	v_mov_b32_dpp v143, v63 row_ror:1 row_mask:0xf bank_mask:0xf
	v_mov_b32_dpp v145, v47 row_shr:2 row_mask:0xf bank_mask:0xf
	v_mov_b32_dpp v142, v55 row_ror:1 row_mask:0xf bank_mask:0xf
	v_mov_b32_dpp v144, v39 row_shr:2 row_mask:0xf bank_mask:0xf
	v_mov_b32_dpp v143, v47 row_shr:1 row_mask:0xf bank_mask:0xf
	v_mov_b32_dpp v142, v39 row_shr:1 row_mask:0xf bank_mask:0xf
	v_pk_fma_f32 v[144:145], v[212:213], v[144:145], v[214:215]
	v_mov_b32_e32 v146, v39
	v_mov_b32_e32 v147, v47
	v_pk_fma_f32 v[142:143], v[210:211], v[142:143], v[144:145]
	v_pk_fma_f32 v[142:143], v[146:147], v[208:209], v[142:143]
	v_mul_f32_e32 v140, 0xbfb8aa3b, v143
	v_exp_f32_e32 v144, v140
	v_mov_b32_dpp v141, v62 row_ror:2 row_mask:0xf bank_mask:0xf
	v_mov_b32_dpp v140, v54 row_ror:2 row_mask:0xf bank_mask:0xf
	v_mov_b32_dpp v139, v62 row_ror:1 row_mask:0xf bank_mask:0xf
	v_mov_b32_dpp v141, v46 row_shr:2 row_mask:0xf bank_mask:0xf
	v_mov_b32_dpp v138, v54 row_ror:1 row_mask:0xf bank_mask:0xf
	v_mov_b32_dpp v140, v38 row_shr:2 row_mask:0xf bank_mask:0xf
	v_mov_b32_dpp v139, v46 row_shr:1 row_mask:0xf bank_mask:0xf
	v_mov_b32_dpp v138, v38 row_shr:1 row_mask:0xf bank_mask:0xf
	v_add_f32_e32 v144, 1.0, v144
	v_pk_fma_f32 v[140:141], v[218:219], v[140:141], v[216:217]
	v_rcp_f32_e32 v146, v144
	v_mov_b32_e32 v144, v38
	v_mov_b32_e32 v145, v46
; DI float frcp(float x) { return __builtin_amdgcn_rcpf(x); }
; DI u32x2 pack4(const f32x4 a) { u32x2 w; w.x = cvt_pk_bf16(a[0], a[1]); w.y = cvt_pk_bf16(a[2], a[3]); return w; }
; template <int N> DI float row_shift(float cur, float prev) {
;     const int t = __builtin_amdgcn_update_dpp(0, __float_as_int(prev), 0x120 + N, 0xf, 0xf, false);
;     return __int_as_float(__builtin_amdgcn_update_dpp(t, __float_as_int(cur), 0x110 + N, 0xf, 0xf, false));
; }
;     DI void operator()(const pg8::f32x4 (&acc)[2][2][4][2], const pg8::Unit& u, int wr, int wc, int fr, int fq) const {
;     ...
;                     const f32x4 cg = acc[ai][0][m][q], cv = acc[ai][1][m][q];
;                     const f32x4 pg = m > 0 ? acc[ai][0][m > 0 ? m - 1 : 0][q] : (f32x4){0.f, 0.f, 0.f, 0.f}, pv = m > 0 ? acc[ai][1][m > 0 ? m - 1 : 0][q] : (f32x4){0.f, 0.f, 0.f, 0.f};
;                     f32x4 o;
; #pragma unroll
;                     for (int e = 0; e < 4; ++e) {
;                         const float g1 = row_shift<1>(cg[e], pg[e]), g2 = row_shift<2>(cg[e], pg[e]), v1 = row_shift<1>(cv[e], pv[e]), v2 = row_shift<2>(cv[e], pv[e]);
;                         const float a = bg[e] + kg0[e] * g2 + kg1[e] * g1 + kg2[e] * cg[e], b = bv[e] + kv0[e] * v2 + kv1[e] * v1 + kv2[e] * cv[e];
;                         o[e] = a * frcp(1.f + __expf(-a)) * b;
;                     }
;                     const int r = u.pm * 256 + ai * 128 + wr * 64 + m * 16 + fr;
;                     if (m > 0 || fr >= 2) *(u32x2*)(ACT + (size_t)r * DFF + j0 + 4 * q) = pack4(o);
	v_pk_fma_f32 v[138:139], v[220:221], v[138:139], v[140:141]
	v_pk_fma_f32 v[138:139], v[144:145], v[222:223], v[138:139]
	v_mul_f32_e32 v140, 0xbfb8aa3b, v139
	v_exp_f32_e32 v140, v140
	v_mov_b32_dpp v137, v61 row_ror:2 row_mask:0xf bank_mask:0xf
	v_mov_b32_dpp v136, v53 row_ror:2 row_mask:0xf bank_mask:0xf
	v_mov_b32_dpp v135, v61 row_ror:1 row_mask:0xf bank_mask:0xf
	v_mov_b32_dpp v137, v45 row_shr:2 row_mask:0xf bank_mask:0xf
	v_mov_b32_dpp v134, v53 row_ror:1 row_mask:0xf bank_mask:0xf
	v_mov_b32_dpp v136, v37 row_shr:2 row_mask:0xf bank_mask:0xf
	v_mov_b32_dpp v135, v45 row_shr:1 row_mask:0xf bank_mask:0xf
	v_mov_b32_dpp v134, v37 row_shr:1 row_mask:0xf bank_mask:0xf
	v_mul_f32_e32 v141, v143, v146
	v_add_f32_e32 v140, 1.0, v140
	v_pk_fma_f32 v[136:137], v[196:197], v[136:137], v[198:199]
	v_mov_b32_dpp v133, v60 row_ror:2 row_mask:0xf bank_mask:0xf
	v_mov_b32_dpp v132, v52 row_ror:2 row_mask:0xf bank_mask:0xf
	v_mul_f32_e32 v142, v142, v141
	v_rcp_f32_e32 v143, v140
	v_mov_b32_e32 v140, v37
	v_mov_b32_e32 v141, v45
	v_pk_fma_f32 v[134:135], v[194:195], v[134:135], v[136:137]
	v_mov_b32_dpp v131, v60 row_ror:1 row_mask:0xf bank_mask:0xf
	v_mov_b32_dpp v133, v44 row_shr:2 row_mask:0xf bank_mask:0xf
	v_mov_b32_dpp v130, v52 row_ror:1 row_mask:0xf bank_mask:0xf
	v_mov_b32_dpp v132, v36 row_shr:2 row_mask:0xf bank_mask:0xf
	v_pk_fma_f32 v[134:135], v[140:141], v[192:193], v[134:135]
	v_mov_b32_dpp v131, v44 row_shr:1 row_mask:0xf bank_mask:0xf
	v_mov_b32_dpp v130, v36 row_shr:1 row_mask:0xf bank_mask:0xf
	v_mul_f32_e32 v136, 0xbfb8aa3b, v135
	v_pk_fma_f32 v[132:133], v[202:203], v[132:133], v[200:201]
	v_exp_f32_e32 v140, v136
	v_mov_b32_e32 v136, v36
	v_mov_b32_e32 v137, v44
	v_pk_fma_f32 v[130:131], v[204:205], v[130:131], v[132:133]
	v_mul_f32_e32 v133, v139, v143
	v_pk_fma_f32 v[130:131], v[136:137], v[206:207], v[130:131]
	v_add_f32_e32 v136, 1.0, v140
	v_mul_f32_e32 v132, 0xbfb8aa3b, v131
	v_exp_f32_e32 v132, v132
	v_rcp_f32_e32 v136, v136
	v_mul_f32_e32 v133, v138, v133
	v_add_f32_e32 v132, 1.0, v132
	v_rcp_f32_e32 v132, v132
	v_mul_f32_e32 v135, v135, v136
	v_mul_f32_e32 v134, v134, v135
	v_add_u32_e32 v135, 0x90, v164
	v_mul_f32_e32 v131, v131, v132
	v_mul_f32_e32 v130, v130, v131
	v_cvt_pk_bf16_f32 v132, v130, v134
	v_mov_b64_e32 v[130:131], s[66:67]
	v_mad_i64_i32 v[134:135], s[14:15], v135, s97, v[130:131]
	v_lshl_add_u64 v[188:189], v[134:135], 0, v[128:129]
	v_cvt_pk_bf16_f32 v133, v133, v142
	global_store_dwordx2 v[188:189], v[132:133], off
	v_mov_b32_dpp v147, v47 row_ror:2 row_mask:0xf bank_mask:0xf
	v_mov_b32_dpp v146, v39 row_ror:2 row_mask:0xf bank_mask:0xf
	v_mov_b32_dpp v145, v47 row_ror:1 row_mask:0xf bank_mask:0xf
	v_mov_b32_dpp v147, v31 row_shr:2 row_mask:0xf bank_mask:0xf
	v_mov_b32_dpp v144, v39 row_ror:1 row_mask:0xf bank_mask:0xf
	v_mov_b32_dpp v146, v23 row_shr:2 row_mask:0xf bank_mask:0xf
	v_mov_b32_dpp v145, v31 row_shr:1 row_mask:0xf bank_mask:0xf
	v_mov_b32_dpp v144, v23 row_shr:1 row_mask:0xf bank_mask:0xf
	v_pk_fma_f32 v[146:147], v[212:213], v[146:147], v[214:215]
	v_mov_b32_e32 v148, v23
	v_mov_b32_e32 v149, v31
	v_pk_fma_f32 v[144:145], v[210:211], v[144:145], v[146:147]
	v_pk_fma_f32 v[144:145], v[148:149], v[208:209], v[144:145]
	v_mul_f32_e32 v142, 0xbfb8aa3b, v145
	v_exp_f32_e32 v146, v142
	v_mov_b32_dpp v143, v46 row_ror:2 row_mask:0xf bank_mask:0xf
	v_mov_b32_dpp v142, v38 row_ror:2 row_mask:0xf bank_mask:0xf
	v_mov_b32_dpp v141, v46 row_ror:1 row_mask:0xf bank_mask:0xf
	v_mov_b32_dpp v143, v30 row_shr:2 row_mask:0xf bank_mask:0xf
	v_mov_b32_dpp v140, v38 row_ror:1 row_mask:0xf bank_mask:0xf
	v_mov_b32_dpp v142, v22 row_shr:2 row_mask:0xf bank_mask:0xf
	v_mov_b32_dpp v141, v30 row_shr:1 row_mask:0xf bank_mask:0xf
	v_mov_b32_dpp v140, v22 row_shr:1 row_mask:0xf bank_mask:0xf
	v_add_f32_e32 v146, 1.0, v146
	v_pk_fma_f32 v[142:143], v[218:219], v[142:143], v[216:217]
	v_rcp_f32_e32 v148, v146
	v_mov_b32_e32 v146, v22
	v_mov_b32_e32 v147, v30
	v_pk_fma_f32 v[140:141], v[220:221], v[140:141], v[142:143]
	v_pk_fma_f32 v[140:141], v[146:147], v[222:223], v[140:141]
	v_mul_f32_e32 v142, 0xbfb8aa3b, v141
	v_exp_f32_e32 v142, v142
	v_mov_b32_dpp v139, v45 row_ror:2 row_mask:0xf bank_mask:0xf
	v_mov_b32_dpp v138, v37 row_ror:2 row_mask:0xf bank_mask:0xf
	v_mov_b32_dpp v137, v45 row_ror:1 row_mask:0xf bank_mask:0xf
	v_mov_b32_dpp v139, v29 row_shr:2 row_mask:0xf bank_mask:0xf
	v_mov_b32_dpp v136, v37 row_ror:1 row_mask:0xf bank_mask:0xf
	v_mov_b32_dpp v138, v21 row_shr:2 row_mask:0xf bank_mask:0xf
	v_mov_b32_dpp v137, v29 row_shr:1 row_mask:0xf bank_mask:0xf
	v_mov_b32_dpp v136, v21 row_shr:1 row_mask:0xf bank_mask:0xf
	v_mul_f32_e32 v143, v145, v148
	v_add_f32_e32 v142, 1.0, v142
	v_pk_fma_f32 v[138:139], v[196:197], v[138:139], v[198:199]
	v_mov_b32_dpp v135, v44 row_ror:2 row_mask:0xf bank_mask:0xf
	v_mov_b32_dpp v134, v36 row_ror:2 row_mask:0xf bank_mask:0xf
	v_mul_f32_e32 v144, v144, v143
	v_rcp_f32_e32 v145, v142
	v_mov_b32_e32 v142, v21
	v_mov_b32_e32 v143, v29
	v_pk_fma_f32 v[136:137], v[194:195], v[136:137], v[138:139]
	v_mov_b32_dpp v133, v44 row_ror:1 row_mask:0xf bank_mask:0xf
	v_mov_b32_dpp v135, v28 row_shr:2 row_mask:0xf bank_mask:0xf
	v_mov_b32_dpp v132, v36 row_ror:1 row_mask:0xf bank_mask:0xf
	v_mov_b32_dpp v134, v20 row_shr:2 row_mask:0xf bank_mask:0xf
	v_pk_fma_f32 v[136:137], v[142:143], v[192:193], v[136:137]
	v_mov_b32_dpp v133, v28 row_shr:1 row_mask:0xf bank_mask:0xf
	v_mov_b32_dpp v132, v20 row_shr:1 row_mask:0xf bank_mask:0xf
	v_mul_f32_e32 v138, 0xbfb8aa3b, v137
	v_pk_fma_f32 v[134:135], v[202:203], v[134:135], v[200:201]
	v_exp_f32_e32 v142, v138
	v_mov_b32_e32 v138, v20
; #define LAS __attribute__((address_space(3)))
; DI float frcp(float x) { return __builtin_amdgcn_rcpf(x); }
; DI u32x2 pack4(const f32x4 a) { u32x2 w; w.x = cvt_pk_bf16(a[0], a[1]); w.y = cvt_pk_bf16(a[2], a[3]); return w; }
;     DI void operator()(const pg8::f32x4 (&acc)[2][2][4][2], const pg8::Unit& u, int wr, int wc, int fr, int fq) const {
;     ...
;         for (int q = 0; q < 2; ++q) {
;             const f32x4 kg0 = *(const LAS f32x4*)(wl + 4 * q), kg1 = *(const LAS f32x4*)(wl + 128 + 4 * q), kg2 = *(const LAS f32x4*)(wl + 256 + 4 * q), bg = *(const LAS f32x4*)(wl + 384 + 4 * q);
;             const f32x4 kv0 = *(const LAS f32x4*)(wl + 512 + 4 * q), kv1 = *(const LAS f32x4*)(wl + 640 + 4 * q), kv2 = *(const LAS f32x4*)(wl + 768 + 4 * q), bv = *(const LAS f32x4*)(wl + 896 + 4 * q);
; #pragma unroll
;             for (int ai = 0; ai < 2; ++ai)
; #pragma unroll
;                 for (int m = 0; m < 4; ++m) {
;                     const f32x4 cg = acc[ai][0][m][q], cv = acc[ai][1][m][q];
;                     const f32x4 pg = m > 0 ? acc[ai][0][m > 0 ? m - 1 : 0][q] : (f32x4){0.f, 0.f, 0.f, 0.f}, pv = m > 0 ? acc[ai][1][m > 0 ? m - 1 : 0][q] : (f32x4){0.f, 0.f, 0.f, 0.f};
;                     f32x4 o;
; #pragma unroll
;                     for (int e = 0; e < 4; ++e) {
;                         const float g1 = row_shift<1>(cg[e], pg[e]), g2 = row_shift<2>(cg[e], pg[e]), v1 = row_shift<1>(cv[e], pv[e]), v2 = row_shift<2>(cv[e], pv[e]);
;                         const float a = bg[e] + kg0[e] * g2 + kg1[e] * g1 + kg2[e] * cg[e], b = bv[e] + kv0[e] * v2 + kv1[e] * v1 + kv2[e] * cv[e];
;                         o[e] = a * frcp(1.f + __expf(-a)) * b;
;                     }
;                     const int r = u.pm * 256 + ai * 128 + wr * 64 + m * 16 + fr;
;                     if (m > 0 || fr >= 2) *(u32x2*)(ACT + (size_t)r * DFF + j0 + 4 * q) = pack4(o);
;                     __builtin_amdgcn_sched_barrier(0);
	v_mov_b32_e32 v139, v28
	v_pk_fma_f32 v[132:133], v[204:205], v[132:133], v[134:135]
	v_mul_f32_e32 v135, v141, v145
	v_pk_fma_f32 v[132:133], v[138:139], v[206:207], v[132:133]
	v_add_f32_e32 v138, 1.0, v142
	v_mul_f32_e32 v134, 0xbfb8aa3b, v133
	v_exp_f32_e32 v134, v134
	v_rcp_f32_e32 v138, v138
	v_mul_f32_e32 v135, v140, v135
	v_add_f32_e32 v134, 1.0, v134
	v_rcp_f32_e32 v134, v134
	v_mul_f32_e32 v137, v137, v138
	v_mul_f32_e32 v136, v136, v137
	v_mul_f32_e32 v133, v133, v134
	v_mul_f32_e32 v132, v132, v133
	v_add_u32_e32 v134, 0xa0, v164
	v_cvt_pk_bf16_f32 v132, v132, v136
	v_cvt_pk_bf16_f32 v133, v135, v144
	v_mad_i64_i32 v[134:135], s[14:15], v134, s97, v[130:131]
	v_lshl_add_u64 v[190:191], v[134:135], 0, v[128:129]
	global_store_dwordx2 v[190:191], v[132:133], off
	v_mov_b32_dpp v147, v31 row_ror:2 row_mask:0xf bank_mask:0xf
	v_mov_b32_dpp v146, v23 row_ror:2 row_mask:0xf bank_mask:0xf
	v_mov_b32_dpp v145, v31 row_ror:1 row_mask:0xf bank_mask:0xf
	v_mov_b32_dpp v147, v15 row_shr:2 row_mask:0xf bank_mask:0xf
	v_mov_b32_dpp v144, v23 row_ror:1 row_mask:0xf bank_mask:0xf
	v_mov_b32_dpp v146, v7 row_shr:2 row_mask:0xf bank_mask:0xf
	v_mov_b32_dpp v145, v15 row_shr:1 row_mask:0xf bank_mask:0xf
	v_mov_b32_dpp v144, v7 row_shr:1 row_mask:0xf bank_mask:0xf
	v_pk_fma_f32 v[146:147], v[212:213], v[146:147], v[214:215]
	v_mov_b32_e32 v148, v7
	v_mov_b32_e32 v149, v15
	v_pk_fma_f32 v[144:145], v[210:211], v[144:145], v[146:147]
	v_pk_fma_f32 v[144:145], v[148:149], v[208:209], v[144:145]
	v_mul_f32_e32 v142, 0xbfb8aa3b, v145
	v_exp_f32_e32 v146, v142
	v_mov_b32_dpp v143, v30 row_ror:2 row_mask:0xf bank_mask:0xf
	v_mov_b32_dpp v142, v22 row_ror:2 row_mask:0xf bank_mask:0xf
	v_mov_b32_dpp v141, v30 row_ror:1 row_mask:0xf bank_mask:0xf
	v_mov_b32_dpp v143, v14 row_shr:2 row_mask:0xf bank_mask:0xf
	v_mov_b32_dpp v140, v22 row_ror:1 row_mask:0xf bank_mask:0xf
	v_mov_b32_dpp v142, v6 row_shr:2 row_mask:0xf bank_mask:0xf
	v_mov_b32_dpp v141, v14 row_shr:1 row_mask:0xf bank_mask:0xf
	v_mov_b32_dpp v140, v6 row_shr:1 row_mask:0xf bank_mask:0xf
	v_add_f32_e32 v146, 1.0, v146
	v_pk_fma_f32 v[142:143], v[218:219], v[142:143], v[216:217]
	v_rcp_f32_e32 v148, v146
	v_mov_b32_e32 v146, v6
	v_mov_b32_e32 v147, v14
	v_pk_fma_f32 v[140:141], v[220:221], v[140:141], v[142:143]
	v_pk_fma_f32 v[140:141], v[146:147], v[222:223], v[140:141]
	v_mul_f32_e32 v142, 0xbfb8aa3b, v141
	v_exp_f32_e32 v142, v142
	v_mov_b32_dpp v139, v29 row_ror:2 row_mask:0xf bank_mask:0xf
	v_mov_b32_dpp v138, v21 row_ror:2 row_mask:0xf bank_mask:0xf
	v_mov_b32_dpp v137, v29 row_ror:1 row_mask:0xf bank_mask:0xf
	v_mov_b32_dpp v139, v13 row_shr:2 row_mask:0xf bank_mask:0xf
	v_mov_b32_dpp v136, v21 row_ror:1 row_mask:0xf bank_mask:0xf
	v_mov_b32_dpp v138, v5 row_shr:2 row_mask:0xf bank_mask:0xf
	v_mov_b32_dpp v137, v13 row_shr:1 row_mask:0xf bank_mask:0xf
	v_mov_b32_dpp v136, v5 row_shr:1 row_mask:0xf bank_mask:0xf
	v_mul_f32_e32 v143, v145, v148
	v_add_f32_e32 v142, 1.0, v142
	v_pk_fma_f32 v[138:139], v[196:197], v[138:139], v[198:199]
	v_mov_b32_dpp v135, v28 row_ror:2 row_mask:0xf bank_mask:0xf
	v_mov_b32_dpp v134, v20 row_ror:2 row_mask:0xf bank_mask:0xf
	v_mul_f32_e32 v144, v144, v143
	v_rcp_f32_e32 v145, v142
	v_mov_b32_e32 v142, v5
	v_mov_b32_e32 v143, v13
	v_pk_fma_f32 v[136:137], v[194:195], v[136:137], v[138:139]
	v_mov_b32_dpp v133, v28 row_ror:1 row_mask:0xf bank_mask:0xf
	v_mov_b32_dpp v135, v12 row_shr:2 row_mask:0xf bank_mask:0xf
	v_mov_b32_dpp v132, v20 row_ror:1 row_mask:0xf bank_mask:0xf
	v_mov_b32_dpp v134, v4 row_shr:2 row_mask:0xf bank_mask:0xf
	v_pk_fma_f32 v[136:137], v[142:143], v[192:193], v[136:137]
	v_mov_b32_dpp v133, v12 row_shr:1 row_mask:0xf bank_mask:0xf
	v_mov_b32_dpp v132, v4 row_shr:1 row_mask:0xf bank_mask:0xf
	v_mul_f32_e32 v138, 0xbfb8aa3b, v137
	v_pk_fma_f32 v[134:135], v[202:203], v[134:135], v[200:201]
	v_exp_f32_e32 v142, v138
	v_mov_b32_e32 v138, v4
	v_mov_b32_e32 v139, v12
	v_pk_fma_f32 v[132:133], v[204:205], v[132:133], v[134:135]
	v_mul_f32_e32 v135, v141, v145
	v_pk_fma_f32 v[132:133], v[138:139], v[206:207], v[132:133]
	v_add_f32_e32 v138, 1.0, v142
	v_mul_f32_e32 v134, 0xbfb8aa3b, v133
	v_exp_f32_e32 v134, v134
	v_rcp_f32_e32 v138, v138
	v_mad_i64_i32 v[130:131], s[14:15], v165, s97, v[130:131]
	v_add_f32_e32 v134, 1.0, v134
	v_rcp_f32_e32 v134, v134
	v_mul_f32_e32 v137, v137, v138
	v_mul_f32_e32 v135, v140, v135
	v_mul_f32_e32 v136, v136, v137
	v_mul_f32_e32 v133, v133, v134
	v_mul_f32_e32 v132, v132, v133
	v_lshl_add_u64 v[192:193], v[130:131], 0, v[128:129]
	v_cvt_pk_bf16_f32 v132, v132, v136
	v_cvt_pk_bf16_f32 v133, v135, v144
	global_store_dwordx2 v[192:193], v[132:133], off
	ds_read_b128 v[148:151], v160 offset:16
	ds_read_b128 v[152:155], v160 offset:528
	ds_read_b128 v[156:159], v160 offset:1040
	ds_read_b128 v[144:147], v160 offset:1552
	ds_read_b128 v[128:131], v160 offset:2064
	ds_read_b128 v[132:135], v160 offset:2576
	ds_read_b128 v[140:143], v160 offset:3088
	ds_read_b128 v[136:139], v160 offset:3600
	v_mov_b32_e32 v236, v161
	v_mov_b32_e32 v240, v161
	s_waitcnt lgkmcnt(4)
; #define LAS __attribute__((address_space(3)))
;     DI void operator()(const pg8::f32x4 (&acc)[2][2][4][2], const pg8::Unit& u, int wr, int wc, int fr, int fq) const {
;     ...
;         for (int q = 0; q < 2; ++q) {
;             const f32x4 kg0 = *(const LAS f32x4*)(wl + 4 * q), kg1 = *(const LAS f32x4*)(wl + 128 + 4 * q), kg2 = *(const LAS f32x4*)(wl + 256 + 4 * q), bg = *(const LAS f32x4*)(wl + 384 + 4 * q);
;             const f32x4 kv0 = *(const LAS f32x4*)(wl + 512 + 4 * q), kv1 = *(const LAS f32x4*)(wl + 640 + 4 * q), kv2 = *(const LAS f32x4*)(wl + 768 + 4 * q), bv = *(const LAS f32x4*)(wl + 896 + 4 * q);
; #pragma unroll
;             for (int ai = 0; ai < 2; ++ai)
; #pragma unroll
;                 for (int m = 0; m < 4; ++m) {
;                     const f32x4 cg = acc[ai][0][m][q], cv = acc[ai][1][m][q];
;                     const f32x4 pg = m > 0 ? acc[ai][0][m > 0 ? m - 1 : 0][q] : (f32x4){0.f, 0.f, 0.f, 0.f}, pv = m > 0 ? acc[ai][1][m > 0 ? m - 1 : 0][q] : (f32x4){0.f, 0.f, 0.f, 0.f};
	v_mov_b32_e32 v203, v144
	v_mov_b32_dpp v236, v236 row_ror:1 row_mask:0xf bank_mask:0xf
	v_mov_b32_dpp v240, v240 row_ror:2 row_mask:0xf bank_mask:0xf
	v_mov_b32_e32 v227, v236
	v_mov_b32_e32 v229, v240
	v_mov_b32_e32 v226, v236
	v_mov_b32_e32 v228, v240
	v_mov_b32_e32 v231, v236
	v_mov_b32_e32 v233, v240
	v_mov_b32_e32 v230, v236
	v_mov_b32_e32 v232, v240
	v_mov_b32_e32 v235, v236
	v_mov_b32_e32 v239, v240
	v_mov_b32_e32 v234, v236
	v_mov_b32_e32 v238, v240
	v_mov_b32_e32 v237, v236
	v_mov_b32_e32 v241, v240
	v_mov_b32_dpp v227, v120 row_shr:1 row_mask:0xf bank_mask:0xf
	v_mov_b32_dpp v229, v120 row_shr:2 row_mask:0xf bank_mask:0xf
	v_mov_b32_dpp v226, v112 row_shr:1 row_mask:0xf bank_mask:0xf
	v_mov_b32_dpp v228, v112 row_shr:2 row_mask:0xf bank_mask:0xf
	v_mov_b32_dpp v231, v121 row_shr:1 row_mask:0xf bank_mask:0xf
	v_mov_b32_dpp v233, v121 row_shr:2 row_mask:0xf bank_mask:0xf
	v_mov_b32_dpp v230, v113 row_shr:1 row_mask:0xf bank_mask:0xf
	v_mov_b32_dpp v232, v113 row_shr:2 row_mask:0xf bank_mask:0xf
	v_mov_b32_dpp v235, v122 row_shr:1 row_mask:0xf bank_mask:0xf
	v_mov_b32_dpp v239, v122 row_shr:2 row_mask:0xf bank_mask:0xf
	v_mov_b32_dpp v234, v114 row_shr:1 row_mask:0xf bank_mask:0xf
	v_mov_b32_dpp v238, v114 row_shr:2 row_mask:0xf bank_mask:0xf
	v_mov_b32_dpp v237, v123 row_shr:1 row_mask:0xf bank_mask:0xf
	v_mov_b32_dpp v241, v123 row_shr:2 row_mask:0xf bank_mask:0xf
	v_mov_b32_dpp v236, v115 row_shr:1 row_mask:0xf bank_mask:0xf
	v_mov_b32_dpp v240, v115 row_shr:2 row_mask:0xf bank_mask:0xf
	s_waitcnt lgkmcnt(0)
	v_mov_b32_e32 v202, v136
	v_mov_b32_e32 v204, v128
	v_mov_b32_e32 v205, v148
	v_mov_b32_e32 v206, v132
	v_mov_b32_e32 v207, v152
	v_mov_b32_e32 v208, v140
	v_mov_b32_e32 v209, v156
	v_mov_b32_e32 v200, v137
	v_mov_b32_e32 v201, v145
	v_mov_b32_e32 v198, v129
	v_mov_b32_e32 v199, v149
	v_mov_b32_e32 v196, v133
	v_mov_b32_e32 v197, v153
	v_mov_b32_e32 v194, v141
	v_mov_b32_e32 v195, v157
	v_mov_b32_e32 v218, v138
	v_mov_b32_e32 v219, v146
	v_mov_b32_e32 v220, v130
	v_mov_b32_e32 v221, v150
	v_mov_b32_e32 v222, v134
	v_mov_b32_e32 v223, v154
	v_mov_b32_e32 v224, v142
	v_mov_b32_e32 v225, v158
	v_mov_b32_e32 v216, v139
	v_mov_b32_e32 v217, v147
	v_mov_b32_e32 v214, v131
	v_mov_b32_e32 v215, v151
	v_mov_b32_e32 v212, v135
	v_mov_b32_e32 v213, v155
	v_mov_b32_e32 v210, v143
	v_mov_b32_e32 v211, v159
	s_and_saveexec_b64 s[14:15], s[38:39]
	s_xor_b64 s[38:39], exec, s[14:15]
	s_cbranch_execz .LBB0_836
	v_mov_b32_e32 v210, v143
	v_mov_b32_e32 v212, v135
	v_mov_b32_e32 v214, v131
	v_mov_b32_e32 v216, v139
	v_mov_b32_e32 v143, v158
	v_mov_b32_e32 v135, v154
	v_mov_b32_e32 v131, v150
	v_mov_b32_e32 v139, v146
	v_mov_b32_e32 v194, v141
	v_mov_b32_e32 v196, v133
	v_mov_b32_e32 v198, v129
	v_mov_b32_e32 v200, v137
	v_mov_b32_e32 v141, v156
	v_mov_b32_e32 v133, v152
	v_mov_b32_e32 v129, v148
	v_mov_b32_e32 v137, v144
	v_mov_b32_e32 v211, v159
	v_mov_b32_e32 v213, v155
	v_mov_b32_e32 v215, v151
	v_mov_b32_e32 v217, v147
	v_mov_b32_e32 v195, v157
	v_mov_b32_e32 v197, v153
	v_mov_b32_e32 v199, v149
	v_mov_b32_e32 v201, v145
	v_mov_b64_e32 v[224:225], v[142:143]
	v_mov_b64_e32 v[222:223], v[134:135]
	v_mov_b64_e32 v[220:221], v[130:131]
	v_mov_b64_e32 v[218:219], v[138:139]
	v_mov_b64_e32 v[208:209], v[140:141]
	v_mov_b64_e32 v[206:207], v[132:133]
	v_mov_b64_e32 v[204:205], v[128:129]
	v_mov_b64_e32 v[202:203], v[136:137]

; DI float frcp(float x) { return __builtin_amdgcn_rcpf(x); }
; DI u32x2 pack4(const f32x4 a) { u32x2 w; w.x = cvt_pk_bf16(a[0], a[1]); w.y = cvt_pk_bf16(a[2], a[3]); return w; }
;     DI void operator()(const pg8::f32x4 (&acc)[2][2][4][2], const pg8::Unit& u, int wr, int wc, int fr, int fq) const {
;     ...
;             for (int ai = 0; ai < 2; ++ai)
; #pragma unroll
;                 for (int m = 0; m < 4; ++m) {
;                     const f32x4 cg = acc[ai][0][m][q], cv = acc[ai][1][m][q];
;                     const f32x4 pg = m > 0 ? acc[ai][0][m > 0 ? m - 1 : 0][q] : (f32x4){0.f, 0.f, 0.f, 0.f}, pv = m > 0 ? acc[ai][1][m > 0 ? m - 1 : 0][q] : (f32x4){0.f, 0.f, 0.f, 0.f};
;                     f32x4 o;
; #pragma unroll
;                     for (int e = 0; e < 4; ++e) {
;                         const float g1 = row_shift<1>(cg[e], pg[e]), g2 = row_shift<2>(cg[e], pg[e]), v1 = row_shift<1>(cv[e], pv[e]), v2 = row_shift<2>(cv[e], pv[e]);
;                         const float a = bg[e] + kg0[e] * g2 + kg1[e] * g1 + kg2[e] * cg[e], b = bv[e] + kv0[e] * v2 + kv1[e] * v1 + kv2[e] * cv[e];
;                         o[e] = a * frcp(1.f + __expf(-a)) * b;
;                     }
;                     const int r = u.pm * 256 + ai * 128 + wr * 64 + m * 16 + fr;
;                     if (m > 0 || fr >= 2) *(u32x2*)(ACT + (size_t)r * DFF + j0 + 4 * q) = pack4(o);
;                     __builtin_amdgcn_sched_barrier(0);
.LBB0_838:
	s_or_b64 exec, exec, s[38:39]
	v_mov_b32_dpp v143, v123 row_ror:2 row_mask:0xf bank_mask:0xf
	v_mov_b32_dpp v142, v115 row_ror:2 row_mask:0xf bank_mask:0xf
	v_mov_b32_dpp v141, v123 row_ror:1 row_mask:0xf bank_mask:0xf
	v_mov_b32_dpp v143, v107 row_shr:2 row_mask:0xf bank_mask:0xf
	v_mov_b32_dpp v140, v115 row_ror:1 row_mask:0xf bank_mask:0xf
	v_mov_b32_dpp v142, v99 row_shr:2 row_mask:0xf bank_mask:0xf
	v_mov_b32_dpp v141, v107 row_shr:1 row_mask:0xf bank_mask:0xf
	v_mov_b32_dpp v140, v99 row_shr:1 row_mask:0xf bank_mask:0xf
	v_pk_fma_f32 v[142:143], v[214:215], v[142:143], v[216:217]
	v_mov_b32_e32 v144, v99
	v_mov_b32_e32 v145, v107
	v_pk_fma_f32 v[140:141], v[212:213], v[140:141], v[142:143]
	v_pk_fma_f32 v[140:141], v[144:145], v[210:211], v[140:141]
	v_mul_f32_e32 v138, 0xbfb8aa3b, v141
	v_exp_f32_e32 v142, v138
	v_mov_b32_dpp v139, v122 row_ror:2 row_mask:0xf bank_mask:0xf
	v_mov_b32_dpp v138, v114 row_ror:2 row_mask:0xf bank_mask:0xf
	v_mov_b32_dpp v137, v122 row_ror:1 row_mask:0xf bank_mask:0xf
	v_mov_b32_dpp v139, v106 row_shr:2 row_mask:0xf bank_mask:0xf
	v_mov_b32_dpp v136, v114 row_ror:1 row_mask:0xf bank_mask:0xf
	v_mov_b32_dpp v138, v98 row_shr:2 row_mask:0xf bank_mask:0xf
	v_mov_b32_dpp v137, v106 row_shr:1 row_mask:0xf bank_mask:0xf
	v_mov_b32_dpp v136, v98 row_shr:1 row_mask:0xf bank_mask:0xf
	v_add_f32_e32 v142, 1.0, v142
	v_pk_fma_f32 v[138:139], v[220:221], v[138:139], v[218:219]
	v_rcp_f32_e32 v144, v142
	v_mov_b32_e32 v142, v98
	v_mov_b32_e32 v143, v106
	v_pk_fma_f32 v[136:137], v[222:223], v[136:137], v[138:139]
	v_pk_fma_f32 v[136:137], v[142:143], v[224:225], v[136:137]
	v_mul_f32_e32 v138, 0xbfb8aa3b, v137
	v_exp_f32_e32 v138, v138
	v_mov_b32_dpp v135, v121 row_ror:2 row_mask:0xf bank_mask:0xf
	v_mov_b32_dpp v134, v113 row_ror:2 row_mask:0xf bank_mask:0xf
	v_mov_b32_dpp v133, v121 row_ror:1 row_mask:0xf bank_mask:0xf
	v_mov_b32_dpp v135, v105 row_shr:2 row_mask:0xf bank_mask:0xf
	v_mov_b32_dpp v132, v113 row_ror:1 row_mask:0xf bank_mask:0xf
	v_mov_b32_dpp v134, v97 row_shr:2 row_mask:0xf bank_mask:0xf
	v_mov_b32_dpp v133, v105 row_shr:1 row_mask:0xf bank_mask:0xf
	v_mov_b32_dpp v132, v97 row_shr:1 row_mask:0xf bank_mask:0xf
	v_mul_f32_e32 v139, v141, v144
	v_add_f32_e32 v138, 1.0, v138
	v_pk_fma_f32 v[134:135], v[198:199], v[134:135], v[200:201]
	v_mov_b32_dpp v131, v120 row_ror:2 row_mask:0xf bank_mask:0xf
	v_mov_b32_dpp v130, v112 row_ror:2 row_mask:0xf bank_mask:0xf
	v_mul_f32_e32 v140, v140, v139
	v_rcp_f32_e32 v141, v138
	v_mov_b32_e32 v138, v97
	v_mov_b32_e32 v139, v105
	v_pk_fma_f32 v[132:133], v[196:197], v[132:133], v[134:135]
	v_mov_b32_dpp v129, v120 row_ror:1 row_mask:0xf bank_mask:0xf
	v_mov_b32_dpp v131, v104 row_shr:2 row_mask:0xf bank_mask:0xf
	v_mov_b32_dpp v128, v112 row_ror:1 row_mask:0xf bank_mask:0xf
	v_mov_b32_dpp v130, v96 row_shr:2 row_mask:0xf bank_mask:0xf
	v_pk_fma_f32 v[132:133], v[138:139], v[194:195], v[132:133]
	v_mov_b32_dpp v129, v104 row_shr:1 row_mask:0xf bank_mask:0xf
	v_mov_b32_dpp v128, v96 row_shr:1 row_mask:0xf bank_mask:0xf
	v_mul_f32_e32 v134, 0xbfb8aa3b, v133
	v_pk_fma_f32 v[130:131], v[204:205], v[130:131], v[202:203]
	v_exp_f32_e32 v138, v134
	v_mov_b32_e32 v134, v96
	v_mov_b32_e32 v135, v104
	v_pk_fma_f32 v[128:129], v[206:207], v[128:129], v[130:131]
	v_mul_f32_e32 v131, v137, v141
	v_pk_fma_f32 v[128:129], v[134:135], v[208:209], v[128:129]
	v_add_f32_e32 v134, 1.0, v138
	v_mul_f32_e32 v130, 0xbfb8aa3b, v129
	v_exp_f32_e32 v130, v130
	v_rcp_f32_e32 v134, v134
	v_mul_f32_e32 v131, v136, v131
	v_add_f32_e32 v130, 1.0, v130
	v_rcp_f32_e32 v130, v130
	v_mul_f32_e32 v133, v133, v134
	v_mul_f32_e32 v132, v132, v133
	v_mul_f32_e32 v129, v129, v130
	v_mul_f32_e32 v128, v128, v129
	v_cvt_pk_bf16_f32 v128, v128, v132
	v_cvt_pk_bf16_f32 v129, v131, v140
	global_store_dwordx2 v[182:183], v[128:129], off offset:8
	v_mov_b32_dpp v143, v107 row_ror:2 row_mask:0xf bank_mask:0xf
	v_mov_b32_dpp v142, v99 row_ror:2 row_mask:0xf bank_mask:0xf
	v_mov_b32_dpp v141, v107 row_ror:1 row_mask:0xf bank_mask:0xf
	v_mov_b32_dpp v143, v91 row_shr:2 row_mask:0xf bank_mask:0xf
	v_mov_b32_dpp v140, v99 row_ror:1 row_mask:0xf bank_mask:0xf
	v_mov_b32_dpp v142, v83 row_shr:2 row_mask:0xf bank_mask:0xf
	v_mov_b32_dpp v141, v91 row_shr:1 row_mask:0xf bank_mask:0xf
	v_mov_b32_dpp v140, v83 row_shr:1 row_mask:0xf bank_mask:0xf
	v_pk_fma_f32 v[142:143], v[214:215], v[142:143], v[216:217]
	v_mov_b32_e32 v144, v83
	v_mov_b32_e32 v145, v91
	v_pk_fma_f32 v[140:141], v[212:213], v[140:141], v[142:143]
	v_pk_fma_f32 v[140:141], v[144:145], v[210:211], v[140:141]
	v_mul_f32_e32 v138, 0xbfb8aa3b, v141
	v_exp_f32_e32 v142, v138
	v_mov_b32_dpp v139, v106 row_ror:2 row_mask:0xf bank_mask:0xf
	v_mov_b32_dpp v138, v98 row_ror:2 row_mask:0xf bank_mask:0xf
	v_mov_b32_dpp v137, v106 row_ror:1 row_mask:0xf bank_mask:0xf
	v_mov_b32_dpp v139, v90 row_shr:2 row_mask:0xf bank_mask:0xf
	v_mov_b32_dpp v136, v98 row_ror:1 row_mask:0xf bank_mask:0xf
	v_mov_b32_dpp v138, v82 row_shr:2 row_mask:0xf bank_mask:0xf
	v_mov_b32_dpp v137, v90 row_shr:1 row_mask:0xf bank_mask:0xf
	v_mov_b32_dpp v136, v82 row_shr:1 row_mask:0xf bank_mask:0xf
	v_add_f32_e32 v142, 1.0, v142
	v_pk_fma_f32 v[138:139], v[220:221], v[138:139], v[218:219]
	v_rcp_f32_e32 v144, v142
	v_mov_b32_e32 v142, v82
	v_mov_b32_e32 v143, v90
	v_pk_fma_f32 v[136:137], v[222:223], v[136:137], v[138:139]
	v_pk_fma_f32 v[136:137], v[142:143], v[224:225], v[136:137]
	v_mul_f32_e32 v138, 0xbfb8aa3b, v137
	v_exp_f32_e32 v138, v138
	v_mov_b32_dpp v135, v105 row_ror:2 row_mask:0xf bank_mask:0xf
	v_mov_b32_dpp v134, v97 row_ror:2 row_mask:0xf bank_mask:0xf
; DI float frcp(float x) { return __builtin_amdgcn_rcpf(x); }
; DI u32x2 pack4(const f32x4 a) { u32x2 w; w.x = cvt_pk_bf16(a[0], a[1]); w.y = cvt_pk_bf16(a[2], a[3]); return w; }
;     DI void operator()(const pg8::f32x4 (&acc)[2][2][4][2], const pg8::Unit& u, int wr, int wc, int fr, int fq) const {
;     ...
;             for (int ai = 0; ai < 2; ++ai)
; #pragma unroll
;                 for (int m = 0; m < 4; ++m) {
;                     const f32x4 cg = acc[ai][0][m][q], cv = acc[ai][1][m][q];
;                     const f32x4 pg = m > 0 ? acc[ai][0][m > 0 ? m - 1 : 0][q] : (f32x4){0.f, 0.f, 0.f, 0.f}, pv = m > 0 ? acc[ai][1][m > 0 ? m - 1 : 0][q] : (f32x4){0.f, 0.f, 0.f, 0.f};
;                     f32x4 o;
; #pragma unroll
;                     for (int e = 0; e < 4; ++e) {
;                         const float g1 = row_shift<1>(cg[e], pg[e]), g2 = row_shift<2>(cg[e], pg[e]), v1 = row_shift<1>(cv[e], pv[e]), v2 = row_shift<2>(cv[e], pv[e]);
;                         const float a = bg[e] + kg0[e] * g2 + kg1[e] * g1 + kg2[e] * cg[e], b = bv[e] + kv0[e] * v2 + kv1[e] * v1 + kv2[e] * cv[e];
;                         o[e] = a * frcp(1.f + __expf(-a)) * b;
;                     }
;                     const int r = u.pm * 256 + ai * 128 + wr * 64 + m * 16 + fr;
;                     if (m > 0 || fr >= 2) *(u32x2*)(ACT + (size_t)r * DFF + j0 + 4 * q) = pack4(o);
;                     __builtin_amdgcn_sched_barrier(0);
	v_mov_b32_dpp v133, v105 row_ror:1 row_mask:0xf bank_mask:0xf
	v_mov_b32_dpp v135, v89 row_shr:2 row_mask:0xf bank_mask:0xf
	v_mov_b32_dpp v132, v97 row_ror:1 row_mask:0xf bank_mask:0xf
	v_mov_b32_dpp v134, v81 row_shr:2 row_mask:0xf bank_mask:0xf
	v_mov_b32_dpp v133, v89 row_shr:1 row_mask:0xf bank_mask:0xf
	v_mov_b32_dpp v132, v81 row_shr:1 row_mask:0xf bank_mask:0xf
	v_mul_f32_e32 v139, v141, v144
	v_add_f32_e32 v138, 1.0, v138
	v_pk_fma_f32 v[134:135], v[198:199], v[134:135], v[200:201]
	v_mov_b32_dpp v131, v104 row_ror:2 row_mask:0xf bank_mask:0xf
	v_mov_b32_dpp v130, v96 row_ror:2 row_mask:0xf bank_mask:0xf
	v_mul_f32_e32 v140, v140, v139
	v_rcp_f32_e32 v141, v138
	v_mov_b32_e32 v138, v81
	v_mov_b32_e32 v139, v89
	v_pk_fma_f32 v[132:133], v[196:197], v[132:133], v[134:135]
	v_mov_b32_dpp v129, v104 row_ror:1 row_mask:0xf bank_mask:0xf
	v_mov_b32_dpp v131, v88 row_shr:2 row_mask:0xf bank_mask:0xf
	v_mov_b32_dpp v128, v96 row_ror:1 row_mask:0xf bank_mask:0xf
	v_mov_b32_dpp v130, v80 row_shr:2 row_mask:0xf bank_mask:0xf
	v_pk_fma_f32 v[132:133], v[138:139], v[194:195], v[132:133]
	v_mov_b32_dpp v129, v88 row_shr:1 row_mask:0xf bank_mask:0xf
	v_mov_b32_dpp v128, v80 row_shr:1 row_mask:0xf bank_mask:0xf
	v_mul_f32_e32 v134, 0xbfb8aa3b, v133
	v_pk_fma_f32 v[130:131], v[204:205], v[130:131], v[202:203]
	v_exp_f32_e32 v138, v134
	v_mov_b32_e32 v134, v80
	v_mov_b32_e32 v135, v88
	v_pk_fma_f32 v[128:129], v[206:207], v[128:129], v[130:131]
	v_mul_f32_e32 v131, v137, v141
	v_pk_fma_f32 v[128:129], v[134:135], v[208:209], v[128:129]
	v_add_f32_e32 v134, 1.0, v138
	v_mul_f32_e32 v130, 0xbfb8aa3b, v129
	v_exp_f32_e32 v130, v130
	v_rcp_f32_e32 v134, v134
	v_mul_f32_e32 v131, v136, v131
	v_add_f32_e32 v130, 1.0, v130
	v_rcp_f32_e32 v130, v130
	v_mul_f32_e32 v133, v133, v134
	v_mul_f32_e32 v132, v132, v133
	v_mul_f32_e32 v129, v129, v130
	v_mul_f32_e32 v128, v128, v129
	v_cvt_pk_bf16_f32 v128, v128, v132
	v_cvt_pk_bf16_f32 v129, v131, v140
	global_store_dwordx2 v[184:185], v[128:129], off offset:8
	v_mov_b32_dpp v143, v91 row_ror:2 row_mask:0xf bank_mask:0xf
	v_mov_b32_dpp v142, v83 row_ror:2 row_mask:0xf bank_mask:0xf
	v_mov_b32_dpp v141, v91 row_ror:1 row_mask:0xf bank_mask:0xf
	v_mov_b32_dpp v143, v75 row_shr:2 row_mask:0xf bank_mask:0xf
	v_mov_b32_dpp v140, v83 row_ror:1 row_mask:0xf bank_mask:0xf
	v_mov_b32_dpp v142, v67 row_shr:2 row_mask:0xf bank_mask:0xf
	v_mov_b32_dpp v141, v75 row_shr:1 row_mask:0xf bank_mask:0xf
	v_mov_b32_dpp v140, v67 row_shr:1 row_mask:0xf bank_mask:0xf
	v_pk_fma_f32 v[142:143], v[214:215], v[142:143], v[216:217]
	v_mov_b32_e32 v144, v67
	v_mov_b32_e32 v145, v75
	v_pk_fma_f32 v[140:141], v[212:213], v[140:141], v[142:143]
	v_pk_fma_f32 v[140:141], v[144:145], v[210:211], v[140:141]
	v_mul_f32_e32 v138, 0xbfb8aa3b, v141
	v_exp_f32_e32 v142, v138
	v_mov_b32_dpp v139, v90 row_ror:2 row_mask:0xf bank_mask:0xf
	v_mov_b32_dpp v138, v82 row_ror:2 row_mask:0xf bank_mask:0xf
	v_mov_b32_dpp v137, v90 row_ror:1 row_mask:0xf bank_mask:0xf
	v_mov_b32_dpp v139, v74 row_shr:2 row_mask:0xf bank_mask:0xf
	v_mov_b32_dpp v136, v82 row_ror:1 row_mask:0xf bank_mask:0xf
	v_mov_b32_dpp v138, v66 row_shr:2 row_mask:0xf bank_mask:0xf
	v_mov_b32_dpp v137, v74 row_shr:1 row_mask:0xf bank_mask:0xf
	v_mov_b32_dpp v136, v66 row_shr:1 row_mask:0xf bank_mask:0xf
	v_add_f32_e32 v142, 1.0, v142
	v_pk_fma_f32 v[138:139], v[220:221], v[138:139], v[218:219]
	v_rcp_f32_e32 v144, v142
	v_mov_b32_e32 v142, v66
	v_mov_b32_e32 v143, v74
	v_pk_fma_f32 v[136:137], v[222:223], v[136:137], v[138:139]
	v_pk_fma_f32 v[136:137], v[142:143], v[224:225], v[136:137]
	v_mul_f32_e32 v138, 0xbfb8aa3b, v137
	v_exp_f32_e32 v138, v138
	v_mov_b32_dpp v135, v89 row_ror:2 row_mask:0xf bank_mask:0xf
	v_mov_b32_dpp v134, v81 row_ror:2 row_mask:0xf bank_mask:0xf
	v_mov_b32_dpp v133, v89 row_ror:1 row_mask:0xf bank_mask:0xf
	v_mov_b32_dpp v135, v73 row_shr:2 row_mask:0xf bank_mask:0xf
	v_mov_b32_dpp v132, v81 row_ror:1 row_mask:0xf bank_mask:0xf
	v_mov_b32_dpp v134, v65 row_shr:2 row_mask:0xf bank_mask:0xf
	v_mov_b32_dpp v133, v73 row_shr:1 row_mask:0xf bank_mask:0xf
	v_mov_b32_dpp v132, v65 row_shr:1 row_mask:0xf bank_mask:0xf
	v_mul_f32_e32 v139, v141, v144
	v_add_f32_e32 v138, 1.0, v138
	v_pk_fma_f32 v[134:135], v[198:199], v[134:135], v[200:201]
	v_mov_b32_dpp v131, v88 row_ror:2 row_mask:0xf bank_mask:0xf
	v_mov_b32_dpp v130, v80 row_ror:2 row_mask:0xf bank_mask:0xf
	v_mul_f32_e32 v140, v140, v139
	v_rcp_f32_e32 v141, v138
	v_mov_b32_e32 v138, v65
	v_mov_b32_e32 v139, v73
	v_pk_fma_f32 v[132:133], v[196:197], v[132:133], v[134:135]
	v_mov_b32_dpp v129, v88 row_ror:1 row_mask:0xf bank_mask:0xf
	v_mov_b32_dpp v131, v72 row_shr:2 row_mask:0xf bank_mask:0xf
	v_mov_b32_dpp v128, v80 row_ror:1 row_mask:0xf bank_mask:0xf
	v_mov_b32_dpp v130, v64 row_shr:2 row_mask:0xf bank_mask:0xf
	v_pk_fma_f32 v[132:133], v[138:139], v[194:195], v[132:133]
	v_mov_b32_dpp v129, v72 row_shr:1 row_mask:0xf bank_mask:0xf
	v_mov_b32_dpp v128, v64 row_shr:1 row_mask:0xf bank_mask:0xf
	v_mul_f32_e32 v134, 0xbfb8aa3b, v133
	v_pk_fma_f32 v[130:131], v[204:205], v[130:131], v[202:203]
	v_exp_f32_e32 v138, v134
	v_mov_b32_e32 v134, v64
	v_mov_b32_e32 v135, v72
	v_pk_fma_f32 v[128:129], v[206:207], v[128:129], v[130:131]
	v_mul_f32_e32 v131, v137, v141
	v_pk_fma_f32 v[128:129], v[134:135], v[208:209], v[128:129]
	v_add_f32_e32 v134, 1.0, v138
	v_mul_f32_e32 v130, 0xbfb8aa3b, v129
	v_exp_f32_e32 v130, v130
	v_rcp_f32_e32 v134, v134
	v_mul_f32_e32 v131, v136, v131
	v_add_f32_e32 v130, 1.0, v130
	v_rcp_f32_e32 v130, v130
	v_mul_f32_e32 v133, v133, v134
	v_mul_f32_e32 v132, v132, v133
	v_mul_f32_e32 v129, v129, v130
; DI float frcp(float x) { return __builtin_amdgcn_rcpf(x); }
; DI u32x2 pack4(const f32x4 a) { u32x2 w; w.x = cvt_pk_bf16(a[0], a[1]); w.y = cvt_pk_bf16(a[2], a[3]); return w; }
;     DI void operator()(const pg8::f32x4 (&acc)[2][2][4][2], const pg8::Unit& u, int wr, int wc, int fr, int fq) const {
;     ...
;                 for (int m = 0; m < 4; ++m) {
;                     const f32x4 cg = acc[ai][0][m][q], cv = acc[ai][1][m][q];
;                     const f32x4 pg = m > 0 ? acc[ai][0][m > 0 ? m - 1 : 0][q] : (f32x4){0.f, 0.f, 0.f, 0.f}, pv = m > 0 ? acc[ai][1][m > 0 ? m - 1 : 0][q] : (f32x4){0.f, 0.f, 0.f, 0.f};
;                     f32x4 o;
; #pragma unroll
;                     for (int e = 0; e < 4; ++e) {
;                         const float g1 = row_shift<1>(cg[e], pg[e]), g2 = row_shift<2>(cg[e], pg[e]), v1 = row_shift<1>(cv[e], pv[e]), v2 = row_shift<2>(cv[e], pv[e]);
;                         const float a = bg[e] + kg0[e] * g2 + kg1[e] * g1 + kg2[e] * cg[e], b = bv[e] + kv0[e] * v2 + kv1[e] * v1 + kv2[e] * cv[e];
;                         o[e] = a * frcp(1.f + __expf(-a)) * b;
;                     }
;                     const int r = u.pm * 256 + ai * 128 + wr * 64 + m * 16 + fr;
;                     if (m > 0 || fr >= 2) *(u32x2*)(ACT + (size_t)r * DFF + j0 + 4 * q) = pack4(o);
;                     __builtin_amdgcn_sched_barrier(0);
	v_mul_f32_e32 v128, v128, v129
	v_cvt_pk_bf16_f32 v128, v128, v132
	v_cvt_pk_bf16_f32 v129, v131, v140
	global_store_dwordx2 v[186:187], v[128:129], off offset:8
	v_mov_b32_e32 v136, v161
	v_mov_b32_e32 v142, v161
	s_nop 0
	v_mov_b32_dpp v136, v136 row_ror:1 row_mask:0xf bank_mask:0xf
	v_mov_b32_dpp v142, v142 row_ror:2 row_mask:0xf bank_mask:0xf
	v_mov_b32_e32 v129, v136
	v_mov_b32_e32 v131, v142
	v_mov_b32_e32 v128, v136
	v_mov_b32_e32 v130, v142
	v_mov_b32_e32 v133, v136
	v_mov_b32_e32 v135, v142
	v_mov_b32_e32 v132, v136
	v_mov_b32_e32 v134, v142
	v_mov_b32_e32 v139, v136
	v_mov_b32_e32 v141, v142
	v_mov_b32_e32 v138, v136
	v_mov_b32_e32 v140, v142
	v_mov_b32_e32 v137, v136
	v_mov_b32_e32 v143, v142
	v_mov_b32_dpp v129, v56 row_shr:1 row_mask:0xf bank_mask:0xf
	v_mov_b32_dpp v131, v56 row_shr:2 row_mask:0xf bank_mask:0xf
	v_mov_b32_dpp v128, v48 row_shr:1 row_mask:0xf bank_mask:0xf
	v_mov_b32_dpp v130, v48 row_shr:2 row_mask:0xf bank_mask:0xf
	v_mov_b32_dpp v133, v57 row_shr:1 row_mask:0xf bank_mask:0xf
	v_mov_b32_dpp v135, v57 row_shr:2 row_mask:0xf bank_mask:0xf
	v_mov_b32_dpp v132, v49 row_shr:1 row_mask:0xf bank_mask:0xf
	v_mov_b32_dpp v134, v49 row_shr:2 row_mask:0xf bank_mask:0xf
	v_mov_b32_dpp v139, v58 row_shr:1 row_mask:0xf bank_mask:0xf
	v_mov_b32_dpp v141, v58 row_shr:2 row_mask:0xf bank_mask:0xf
	v_mov_b32_dpp v138, v50 row_shr:1 row_mask:0xf bank_mask:0xf
	v_mov_b32_dpp v140, v50 row_shr:2 row_mask:0xf bank_mask:0xf
	v_mov_b32_dpp v137, v59 row_shr:1 row_mask:0xf bank_mask:0xf
	v_mov_b32_dpp v143, v59 row_shr:2 row_mask:0xf bank_mask:0xf
	v_mov_b32_dpp v136, v51 row_shr:1 row_mask:0xf bank_mask:0xf
	v_mov_b32_dpp v142, v51 row_shr:2 row_mask:0xf bank_mask:0xf
	s_and_saveexec_b64 s[38:39], vcc
	s_cbranch_execz .LBB0_840
	v_pk_fma_f32 v[142:143], v[214:215], v[142:143], v[216:217]
	v_mov_b32_e32 v144, v51
	v_mov_b32_e32 v145, v59
	v_pk_fma_f32 v[136:137], v[212:213], v[136:137], v[142:143]
	v_pk_fma_f32 v[140:141], v[220:221], v[140:141], v[218:219]
	v_pk_fma_f32 v[136:137], v[144:145], v[210:211], v[136:137]
	v_pk_fma_f32 v[138:139], v[222:223], v[138:139], v[140:141]
	v_mul_f32_e32 v142, 0xbfb8aa3b, v137
	v_exp_f32_e32 v143, v142
	v_mov_b32_e32 v142, v50
	v_pk_fma_f32 v[134:135], v[198:199], v[134:135], v[200:201]
	v_pk_fma_f32 v[130:131], v[204:205], v[130:131], v[202:203]
	v_add_f32_e32 v143, 1.0, v143
	v_rcp_f32_e32 v144, v143
	v_mov_b32_e32 v143, v58
	v_pk_fma_f32 v[138:139], v[142:143], v[224:225], v[138:139]
	v_pk_fma_f32 v[132:133], v[196:197], v[132:133], v[134:135]
	v_mul_f32_e32 v140, 0xbfb8aa3b, v139
	v_exp_f32_e32 v140, v140
	v_mul_f32_e32 v137, v137, v144
	v_mul_f32_e32 v141, v136, v137
	v_mov_b32_e32 v137, v57
	v_add_f32_e32 v136, 1.0, v140
	v_rcp_f32_e32 v140, v136
	v_mov_b32_e32 v136, v49
	v_pk_fma_f32 v[132:133], v[136:137], v[194:195], v[132:133]
	v_mov_b32_e32 v135, v56
	v_mul_f32_e32 v134, 0xbfb8aa3b, v133
	v_exp_f32_e32 v136, v134
	v_mov_b32_e32 v134, v48
	v_pk_fma_f32 v[128:129], v[206:207], v[128:129], v[130:131]
	v_mul_f32_e32 v131, v139, v140
	v_pk_fma_f32 v[128:129], v[134:135], v[208:209], v[128:129]
	v_add_f32_e32 v134, 1.0, v136
	v_mul_f32_e32 v130, 0xbfb8aa3b, v129
	v_exp_f32_e32 v130, v130
	v_rcp_f32_e32 v134, v134
	v_mul_f32_e32 v131, v138, v131
	v_add_f32_e32 v130, 1.0, v130
	v_rcp_f32_e32 v130, v130
	v_mul_f32_e32 v133, v133, v134
	v_mul_f32_e32 v132, v132, v133
	v_mul_f32_e32 v129, v129, v130
	v_mul_f32_e32 v128, v128, v129
	v_cvt_pk_bf16_f32 v128, v128, v132
	v_cvt_pk_bf16_f32 v129, v131, v141
	v_mov_b64_e32 v[130:131], s[66:67]
	v_mad_i64_i32 v[130:131], s[14:15], v163, s97, v[130:131]
	v_lshl_add_u64 v[130:131], v[178:179], 1, v[130:131]
	global_store_dwordx2 v[130:131], v[128:129], off offset:8
.LBB0_840:
	s_or_b64 exec, exec, s[38:39]
	v_mov_b32_dpp v143, v59 row_ror:2 row_mask:0xf bank_mask:0xf
	v_mov_b32_dpp v142, v51 row_ror:2 row_mask:0xf bank_mask:0xf
	v_mov_b32_dpp v141, v59 row_ror:1 row_mask:0xf bank_mask:0xf
	v_mov_b32_dpp v143, v43 row_shr:2 row_mask:0xf bank_mask:0xf
	v_mov_b32_dpp v140, v51 row_ror:1 row_mask:0xf bank_mask:0xf
	v_mov_b32_dpp v142, v35 row_shr:2 row_mask:0xf bank_mask:0xf
	v_mov_b32_dpp v141, v43 row_shr:1 row_mask:0xf bank_mask:0xf
	v_mov_b32_dpp v140, v35 row_shr:1 row_mask:0xf bank_mask:0xf
	v_pk_fma_f32 v[142:143], v[214:215], v[142:143], v[216:217]
	v_mov_b32_e32 v144, v35
	v_mov_b32_e32 v145, v43
	v_pk_fma_f32 v[140:141], v[212:213], v[140:141], v[142:143]
	v_pk_fma_f32 v[140:141], v[144:145], v[210:211], v[140:141]
	v_mul_f32_e32 v138, 0xbfb8aa3b, v141
	v_exp_f32_e32 v142, v138
	v_mov_b32_dpp v139, v58 row_ror:2 row_mask:0xf bank_mask:0xf
	v_mov_b32_dpp v138, v50 row_ror:2 row_mask:0xf bank_mask:0xf
	v_mov_b32_dpp v137, v58 row_ror:1 row_mask:0xf bank_mask:0xf
	v_mov_b32_dpp v139, v42 row_shr:2 row_mask:0xf bank_mask:0xf
	v_mov_b32_dpp v136, v50 row_ror:1 row_mask:0xf bank_mask:0xf
	v_mov_b32_dpp v138, v34 row_shr:2 row_mask:0xf bank_mask:0xf
	v_mov_b32_dpp v137, v42 row_shr:1 row_mask:0xf bank_mask:0xf
	v_mov_b32_dpp v136, v34 row_shr:1 row_mask:0xf bank_mask:0xf
	v_add_f32_e32 v142, 1.0, v142
	v_pk_fma_f32 v[138:139], v[220:221], v[138:139], v[218:219]
	v_rcp_f32_e32 v144, v142
	v_mov_b32_e32 v142, v34
	v_mov_b32_e32 v143, v42
	v_pk_fma_f32 v[136:137], v[222:223], v[136:137], v[138:139]
	v_pk_fma_f32 v[136:137], v[142:143], v[224:225], v[136:137]
	v_mul_f32_e32 v138, 0xbfb8aa3b, v137
	v_exp_f32_e32 v138, v138
	v_mov_b32_dpp v135, v57 row_ror:2 row_mask:0xf bank_mask:0xf
	v_mov_b32_dpp v134, v49 row_ror:2 row_mask:0xf bank_mask:0xf
	v_mov_b32_dpp v133, v57 row_ror:1 row_mask:0xf bank_mask:0xf
	v_mov_b32_dpp v135, v41 row_shr:2 row_mask:0xf bank_mask:0xf
; DI float frcp(float x) { return __builtin_amdgcn_rcpf(x); }
; DI u32x2 pack4(const f32x4 a) { u32x2 w; w.x = cvt_pk_bf16(a[0], a[1]); w.y = cvt_pk_bf16(a[2], a[3]); return w; }
;     DI void operator()(const pg8::f32x4 (&acc)[2][2][4][2], const pg8::Unit& u, int wr, int wc, int fr, int fq) const {
;     ...
;             for (int ai = 0; ai < 2; ++ai)
; #pragma unroll
;                 for (int m = 0; m < 4; ++m) {
;                     const f32x4 cg = acc[ai][0][m][q], cv = acc[ai][1][m][q];
;                     const f32x4 pg = m > 0 ? acc[ai][0][m > 0 ? m - 1 : 0][q] : (f32x4){0.f, 0.f, 0.f, 0.f}, pv = m > 0 ? acc[ai][1][m > 0 ? m - 1 : 0][q] : (f32x4){0.f, 0.f, 0.f, 0.f};
;                     f32x4 o;
; #pragma unroll
;                     for (int e = 0; e < 4; ++e) {
;                         const float g1 = row_shift<1>(cg[e], pg[e]), g2 = row_shift<2>(cg[e], pg[e]), v1 = row_shift<1>(cv[e], pv[e]), v2 = row_shift<2>(cv[e], pv[e]);
;                         const float a = bg[e] + kg0[e] * g2 + kg1[e] * g1 + kg2[e] * cg[e], b = bv[e] + kv0[e] * v2 + kv1[e] * v1 + kv2[e] * cv[e];
;                         o[e] = a * frcp(1.f + __expf(-a)) * b;
;                     }
;                     const int r = u.pm * 256 + ai * 128 + wr * 64 + m * 16 + fr;
;                     if (m > 0 || fr >= 2) *(u32x2*)(ACT + (size_t)r * DFF + j0 + 4 * q) = pack4(o);
;                     __builtin_amdgcn_sched_barrier(0);
	v_mov_b32_dpp v132, v49 row_ror:1 row_mask:0xf bank_mask:0xf
	v_mov_b32_dpp v134, v33 row_shr:2 row_mask:0xf bank_mask:0xf
	v_mov_b32_dpp v133, v41 row_shr:1 row_mask:0xf bank_mask:0xf
	v_mov_b32_dpp v132, v33 row_shr:1 row_mask:0xf bank_mask:0xf
	v_mul_f32_e32 v139, v141, v144
	v_add_f32_e32 v138, 1.0, v138
	v_pk_fma_f32 v[134:135], v[198:199], v[134:135], v[200:201]
	v_mov_b32_dpp v131, v56 row_ror:2 row_mask:0xf bank_mask:0xf
	v_mov_b32_dpp v130, v48 row_ror:2 row_mask:0xf bank_mask:0xf
	v_mul_f32_e32 v140, v140, v139
	v_rcp_f32_e32 v141, v138
	v_mov_b32_e32 v138, v33
	v_mov_b32_e32 v139, v41
	v_pk_fma_f32 v[132:133], v[196:197], v[132:133], v[134:135]
	v_mov_b32_dpp v129, v56 row_ror:1 row_mask:0xf bank_mask:0xf
	v_mov_b32_dpp v131, v40 row_shr:2 row_mask:0xf bank_mask:0xf
	v_mov_b32_dpp v128, v48 row_ror:1 row_mask:0xf bank_mask:0xf
	v_mov_b32_dpp v130, v32 row_shr:2 row_mask:0xf bank_mask:0xf
	v_pk_fma_f32 v[132:133], v[138:139], v[194:195], v[132:133]
	v_mov_b32_dpp v129, v40 row_shr:1 row_mask:0xf bank_mask:0xf
	v_mov_b32_dpp v128, v32 row_shr:1 row_mask:0xf bank_mask:0xf
	v_mul_f32_e32 v134, 0xbfb8aa3b, v133
	v_pk_fma_f32 v[130:131], v[204:205], v[130:131], v[202:203]
	v_exp_f32_e32 v138, v134
	v_mov_b32_e32 v134, v32
	v_mov_b32_e32 v135, v40
	v_pk_fma_f32 v[128:129], v[206:207], v[128:129], v[130:131]
	v_mul_f32_e32 v131, v137, v141
	v_pk_fma_f32 v[128:129], v[134:135], v[208:209], v[128:129]
	v_add_f32_e32 v134, 1.0, v138
	v_mul_f32_e32 v130, 0xbfb8aa3b, v129
	v_exp_f32_e32 v130, v130
	v_rcp_f32_e32 v134, v134
	v_mul_f32_e32 v131, v136, v131
	v_add_f32_e32 v130, 1.0, v130
	v_rcp_f32_e32 v130, v130
	v_mul_f32_e32 v133, v133, v134
	v_mul_f32_e32 v132, v132, v133
	v_mul_f32_e32 v129, v129, v130
	v_mul_f32_e32 v128, v128, v129
	v_cvt_pk_bf16_f32 v128, v128, v132
	v_cvt_pk_bf16_f32 v129, v131, v140
	global_store_dwordx2 v[188:189], v[128:129], off offset:8
	v_mov_b32_dpp v143, v43 row_ror:2 row_mask:0xf bank_mask:0xf
	v_mov_b32_dpp v142, v35 row_ror:2 row_mask:0xf bank_mask:0xf
	v_mov_b32_dpp v141, v43 row_ror:1 row_mask:0xf bank_mask:0xf
	v_mov_b32_dpp v143, v27 row_shr:2 row_mask:0xf bank_mask:0xf
	v_mov_b32_dpp v140, v35 row_ror:1 row_mask:0xf bank_mask:0xf
	v_mov_b32_dpp v142, v19 row_shr:2 row_mask:0xf bank_mask:0xf
	v_mov_b32_dpp v141, v27 row_shr:1 row_mask:0xf bank_mask:0xf
	v_mov_b32_dpp v140, v19 row_shr:1 row_mask:0xf bank_mask:0xf
	v_pk_fma_f32 v[142:143], v[214:215], v[142:143], v[216:217]
	v_mov_b32_e32 v144, v19
	v_mov_b32_e32 v145, v27
	v_pk_fma_f32 v[140:141], v[212:213], v[140:141], v[142:143]
	v_pk_fma_f32 v[140:141], v[144:145], v[210:211], v[140:141]
	v_mul_f32_e32 v138, 0xbfb8aa3b, v141
	v_exp_f32_e32 v142, v138
	v_mov_b32_dpp v139, v42 row_ror:2 row_mask:0xf bank_mask:0xf
	v_mov_b32_dpp v138, v34 row_ror:2 row_mask:0xf bank_mask:0xf
	v_mov_b32_dpp v137, v42 row_ror:1 row_mask:0xf bank_mask:0xf
	v_mov_b32_dpp v139, v26 row_shr:2 row_mask:0xf bank_mask:0xf
	v_mov_b32_dpp v136, v34 row_ror:1 row_mask:0xf bank_mask:0xf
	v_mov_b32_dpp v138, v18 row_shr:2 row_mask:0xf bank_mask:0xf
	v_mov_b32_dpp v137, v26 row_shr:1 row_mask:0xf bank_mask:0xf
	v_mov_b32_dpp v136, v18 row_shr:1 row_mask:0xf bank_mask:0xf
	v_add_f32_e32 v142, 1.0, v142
	v_pk_fma_f32 v[138:139], v[220:221], v[138:139], v[218:219]
	v_rcp_f32_e32 v144, v142
	v_mov_b32_e32 v142, v18
	v_mov_b32_e32 v143, v26
	v_pk_fma_f32 v[136:137], v[222:223], v[136:137], v[138:139]
	v_pk_fma_f32 v[136:137], v[142:143], v[224:225], v[136:137]
	v_mul_f32_e32 v138, 0xbfb8aa3b, v137
	v_exp_f32_e32 v138, v138
	v_mov_b32_dpp v135, v41 row_ror:2 row_mask:0xf bank_mask:0xf
	v_mov_b32_dpp v134, v33 row_ror:2 row_mask:0xf bank_mask:0xf
	v_mov_b32_dpp v133, v41 row_ror:1 row_mask:0xf bank_mask:0xf
	v_mov_b32_dpp v135, v25 row_shr:2 row_mask:0xf bank_mask:0xf
	v_mov_b32_dpp v132, v33 row_ror:1 row_mask:0xf bank_mask:0xf
	v_mov_b32_dpp v134, v17 row_shr:2 row_mask:0xf bank_mask:0xf
	v_mov_b32_dpp v133, v25 row_shr:1 row_mask:0xf bank_mask:0xf
	v_mov_b32_dpp v132, v17 row_shr:1 row_mask:0xf bank_mask:0xf
	v_mul_f32_e32 v139, v141, v144
	v_add_f32_e32 v138, 1.0, v138
	v_pk_fma_f32 v[134:135], v[198:199], v[134:135], v[200:201]
	v_mov_b32_dpp v131, v40 row_ror:2 row_mask:0xf bank_mask:0xf
	v_mov_b32_dpp v130, v32 row_ror:2 row_mask:0xf bank_mask:0xf
	v_mul_f32_e32 v140, v140, v139
	v_rcp_f32_e32 v141, v138
	v_mov_b32_e32 v138, v17
	v_mov_b32_e32 v139, v25
	v_pk_fma_f32 v[132:133], v[196:197], v[132:133], v[134:135]
	v_mov_b32_dpp v129, v40 row_ror:1 row_mask:0xf bank_mask:0xf
	v_mov_b32_dpp v131, v24 row_shr:2 row_mask:0xf bank_mask:0xf
	v_mov_b32_dpp v128, v32 row_ror:1 row_mask:0xf bank_mask:0xf
	v_mov_b32_dpp v130, v16 row_shr:2 row_mask:0xf bank_mask:0xf
; DI float frcp(float x) { return __builtin_amdgcn_rcpf(x); }
; DI u32x2 pack4(const f32x4 a) { u32x2 w; w.x = cvt_pk_bf16(a[0], a[1]); w.y = cvt_pk_bf16(a[2], a[3]); return w; }
;     DI void operator()(const pg8::f32x4 (&acc)[2][2][4][2], const pg8::Unit& u, int wr, int wc, int fr, int fq) const {
;     ...
;             for (int ai = 0; ai < 2; ++ai)
; #pragma unroll
;                 for (int m = 0; m < 4; ++m) {
;                     const f32x4 cg = acc[ai][0][m][q], cv = acc[ai][1][m][q];
;                     const f32x4 pg = m > 0 ? acc[ai][0][m > 0 ? m - 1 : 0][q] : (f32x4){0.f, 0.f, 0.f, 0.f}, pv = m > 0 ? acc[ai][1][m > 0 ? m - 1 : 0][q] : (f32x4){0.f, 0.f, 0.f, 0.f};
;                     f32x4 o;
; #pragma unroll
;                     for (int e = 0; e < 4; ++e) {
;                         const float g1 = row_shift<1>(cg[e], pg[e]), g2 = row_shift<2>(cg[e], pg[e]), v1 = row_shift<1>(cv[e], pv[e]), v2 = row_shift<2>(cv[e], pv[e]);
;                         const float a = bg[e] + kg0[e] * g2 + kg1[e] * g1 + kg2[e] * cg[e], b = bv[e] + kv0[e] * v2 + kv1[e] * v1 + kv2[e] * cv[e];
;                         o[e] = a * frcp(1.f + __expf(-a)) * b;
;                     }
;                     const int r = u.pm * 256 + ai * 128 + wr * 64 + m * 16 + fr;
;                     if (m > 0 || fr >= 2) *(u32x2*)(ACT + (size_t)r * DFF + j0 + 4 * q) = pack4(o);
;                     __builtin_amdgcn_sched_barrier(0);
	v_pk_fma_f32 v[132:133], v[138:139], v[194:195], v[132:133]
	v_mov_b32_dpp v129, v24 row_shr:1 row_mask:0xf bank_mask:0xf
	v_mov_b32_dpp v128, v16 row_shr:1 row_mask:0xf bank_mask:0xf
	v_mul_f32_e32 v134, 0xbfb8aa3b, v133
	v_pk_fma_f32 v[130:131], v[204:205], v[130:131], v[202:203]
	v_exp_f32_e32 v138, v134
	v_mov_b32_e32 v134, v16
	v_mov_b32_e32 v135, v24
	v_pk_fma_f32 v[128:129], v[206:207], v[128:129], v[130:131]
	v_mul_f32_e32 v131, v137, v141
	v_pk_fma_f32 v[128:129], v[134:135], v[208:209], v[128:129]
	v_add_f32_e32 v134, 1.0, v138
	v_mul_f32_e32 v130, 0xbfb8aa3b, v129
	v_exp_f32_e32 v130, v130
	v_rcp_f32_e32 v134, v134
	v_mul_f32_e32 v131, v136, v131
	v_add_f32_e32 v130, 1.0, v130
	v_rcp_f32_e32 v130, v130
	v_mul_f32_e32 v133, v133, v134
	v_mul_f32_e32 v132, v132, v133
	v_mul_f32_e32 v129, v129, v130
	v_mul_f32_e32 v128, v128, v129
	v_cvt_pk_bf16_f32 v128, v128, v132
	v_cvt_pk_bf16_f32 v129, v131, v140
	global_store_dwordx2 v[190:191], v[128:129], off offset:8
	v_mov_b32_dpp v143, v27 row_ror:2 row_mask:0xf bank_mask:0xf
	v_mov_b32_dpp v142, v19 row_ror:2 row_mask:0xf bank_mask:0xf
	v_mov_b32_dpp v141, v27 row_ror:1 row_mask:0xf bank_mask:0xf
	v_mov_b32_dpp v143, v11 row_shr:2 row_mask:0xf bank_mask:0xf
	v_mov_b32_dpp v140, v19 row_ror:1 row_mask:0xf bank_mask:0xf
	v_mov_b32_dpp v142, v3 row_shr:2 row_mask:0xf bank_mask:0xf
	v_mov_b32_dpp v141, v11 row_shr:1 row_mask:0xf bank_mask:0xf
	v_mov_b32_dpp v140, v3 row_shr:1 row_mask:0xf bank_mask:0xf
	v_pk_fma_f32 v[142:143], v[214:215], v[142:143], v[216:217]
	v_mov_b32_e32 v144, v3
	v_mov_b32_e32 v145, v11
	v_pk_fma_f32 v[140:141], v[212:213], v[140:141], v[142:143]
	v_pk_fma_f32 v[140:141], v[144:145], v[210:211], v[140:141]
	v_mul_f32_e32 v138, 0xbfb8aa3b, v141
	v_exp_f32_e32 v142, v138
	v_mov_b32_dpp v139, v26 row_ror:2 row_mask:0xf bank_mask:0xf
	v_mov_b32_dpp v138, v18 row_ror:2 row_mask:0xf bank_mask:0xf
	v_mov_b32_dpp v137, v26 row_ror:1 row_mask:0xf bank_mask:0xf
	v_mov_b32_dpp v139, v10 row_shr:2 row_mask:0xf bank_mask:0xf
	v_mov_b32_dpp v136, v18 row_ror:1 row_mask:0xf bank_mask:0xf
	v_mov_b32_dpp v138, v2 row_shr:2 row_mask:0xf bank_mask:0xf
	v_mov_b32_dpp v137, v10 row_shr:1 row_mask:0xf bank_mask:0xf
	v_mov_b32_dpp v136, v2 row_shr:1 row_mask:0xf bank_mask:0xf
	v_add_f32_e32 v142, 1.0, v142
	v_pk_fma_f32 v[138:139], v[220:221], v[138:139], v[218:219]
	v_rcp_f32_e32 v144, v142
	v_mov_b32_e32 v142, v2
	v_mov_b32_e32 v143, v10
	v_pk_fma_f32 v[136:137], v[222:223], v[136:137], v[138:139]
	v_pk_fma_f32 v[136:137], v[142:143], v[224:225], v[136:137]
	v_mul_f32_e32 v138, 0xbfb8aa3b, v137
	v_exp_f32_e32 v138, v138
	v_mov_b32_dpp v135, v25 row_ror:2 row_mask:0xf bank_mask:0xf
	v_mov_b32_dpp v134, v17 row_ror:2 row_mask:0xf bank_mask:0xf
	v_mov_b32_dpp v133, v25 row_ror:1 row_mask:0xf bank_mask:0xf
	v_mov_b32_dpp v135, v9 row_shr:2 row_mask:0xf bank_mask:0xf
	v_mov_b32_dpp v132, v17 row_ror:1 row_mask:0xf bank_mask:0xf
	v_mov_b32_dpp v134, v1 row_shr:2 row_mask:0xf bank_mask:0xf
	v_mov_b32_dpp v133, v9 row_shr:1 row_mask:0xf bank_mask:0xf
	v_mov_b32_dpp v132, v1 row_shr:1 row_mask:0xf bank_mask:0xf
	v_mul_f32_e32 v139, v141, v144
	v_add_f32_e32 v138, 1.0, v138
	v_pk_fma_f32 v[134:135], v[198:199], v[134:135], v[200:201]
	v_mov_b32_dpp v131, v24 row_ror:2 row_mask:0xf bank_mask:0xf
	v_mov_b32_dpp v130, v16 row_ror:2 row_mask:0xf bank_mask:0xf
	v_mul_f32_e32 v140, v140, v139
	v_rcp_f32_e32 v141, v138
	v_mov_b32_e32 v138, v1
	v_mov_b32_e32 v139, v9
	v_pk_fma_f32 v[132:133], v[196:197], v[132:133], v[134:135]
	v_mov_b32_dpp v129, v24 row_ror:1 row_mask:0xf bank_mask:0xf
	v_mov_b32_dpp v131, v8 row_shr:2 row_mask:0xf bank_mask:0xf
	v_mov_b32_dpp v128, v16 row_ror:1 row_mask:0xf bank_mask:0xf
	v_mov_b32_dpp v130, v0 row_shr:2 row_mask:0xf bank_mask:0xf
	v_pk_fma_f32 v[132:133], v[138:139], v[194:195], v[132:133]
	v_mov_b32_dpp v129, v8 row_shr:1 row_mask:0xf bank_mask:0xf
	v_mov_b32_dpp v128, v0 row_shr:1 row_mask:0xf bank_mask:0xf
	v_mul_f32_e32 v134, 0xbfb8aa3b, v133
	v_pk_fma_f32 v[130:131], v[204:205], v[130:131], v[202:203]
	v_exp_f32_e32 v138, v134
	v_mov_b32_e32 v134, v0
	v_mov_b32_e32 v135, v8
	v_pk_fma_f32 v[128:129], v[206:207], v[128:129], v[130:131]
	v_mul_f32_e32 v131, v137, v141
	v_pk_fma_f32 v[128:129], v[134:135], v[208:209], v[128:129]
	v_add_f32_e32 v134, 1.0, v138
	v_mul_f32_e32 v130, 0xbfb8aa3b, v129
	v_exp_f32_e32 v130, v130
	v_rcp_f32_e32 v134, v134
	v_mul_f32_e32 v131, v136, v131
	v_add_f32_e32 v130, 1.0, v130
	v_rcp_f32_e32 v130, v130
	v_mul_f32_e32 v133, v133, v134
	v_mul_f32_e32 v132, v132, v133
	v_mul_f32_e32 v129, v129, v130
	v_mul_f32_e32 v128, v128, v129
	v_cvt_pk_bf16_f32 v128, v128, v132
	v_cvt_pk_bf16_f32 v129, v131, v140
	global_store_dwordx2 v[192:193], v[128:129], off offset:8
